# recurrence: per-step LDS waits split (operands needed early vs b/r needed after the reduce), counted against the in-order queue instead of one wait at the step top
# baseline (speedup 1.0000x reference)
; #define LAS __attribute__((address_space(3)))
; DI unsigned pk2(float a, float b) { f32x2 v = {a, b}; bf2_t r = __builtin_convertvector(v, bf2_t); return __builtin_bit_cast(unsigned, r); }
; DI f32x2 red16p(f32x2 x) { float a = x.x, b = x.y; red16x2(a, b); return (f32x2){a, b}; }
; DI void scan_bh2(const Args& a, int l, int bh, int halfsel, LAS unsigned char* lds) {
;     ...
;         for (int c = 0; c < SEQ / T; ++c) {
;             const LAS float* cur = opbuf + (c & 1) * CH;
;             LAS unsigned char* yb = ybuf + (c & 1) * (T * 128);
;             f32x4 r4 = *(const LAS f32x4*)(cur + kq * 4), d4 = *(const LAS f32x4*)(cur + 64 + kq * 4), k4 = *(const LAS f32x4*)(cur + 128 + kq * 4),
;                   kk4 = *(const LAS f32x4*)(cur + 192 + kq * 4), b4 = *(const LAS f32x4*)(cur + 256 + kq * 4);
;             f32x2 v2 = *(const LAS f32x2*)(cur + 320 + row0);
; #pragma unroll
;             for (int st = 0; st < T; ++st) {
;                 f32x4 nr4, nd4, nk4, nkk4, nb4; f32x2 nv2;
;                 if (st < T - 1) {
;                     const LAS float* o = cur + (st + 1) * 384;
;                     nr4 = *(const LAS f32x4*)(o + kq * 4); nd4 = *(const LAS f32x4*)(o + 64 + kq * 4); nk4 = *(const LAS f32x4*)(o + 128 + kq * 4);
;                     nkk4 = *(const LAS f32x4*)(o + 192 + kq * 4); nb4 = *(const LAS f32x4*)(o + 256 + kq * 4); nv2 = *(const LAS f32x2*)(o + 320 + row0);
;                 }
;                 f32x2 sa = S[0] * kk4[0]; sa += S[1] * kk4[1]; f32x2 sb = S[2] * kk4[2]; sb += S[3] * kk4[3]; sa += sb;
;                 sa = red16p(sa); sa = -sa;
; #pragma unroll
;                 for (int j = 0; j < 4; ++j) S[j] = S[j] * d4[j] + sa * b4[j] + v2 * k4[j];
;                 f32x2 y = S[0] * r4[0]; y += S[1] * r4[1]; f32x2 yc = S[2] * r4[2]; yc += S[3] * r4[3]; y += yc;
;                 y = red16p(y);
;                 *(LAS unsigned*)(yb + st * 128 + row0 * 2) = pk2(y.x, y.y);
.LBB0_497:
	s_and_b32 s2, s4, 1
	s_mul_i32 s3, s2, 0xc000
	s_lshl_b32 s2, s2, 12
	s_add_i32 s5, s2, 0x18000
	v_lshrrev_b32_e32 v254, 2, v11
	v_xor_b32_e32 v254, v254, v11
	v_bfe_u32 v254, v254, 2, 1
	v_add_u32_e32 v255, v10, v254
	v_xor_b32_e32 v254, 1, v254
	v_add_u32_e32 v254, v10, v254
	v_lshl_add_u32 v250, v11, 2, s3
	v_lshl_add_u32 v251, v255, 2, s3
	v_lshl_add_u32 v252, v254, 2, s3
	v_sub_u32_e32 v254, v255, v10
	v_lshl_add_u32 v253, v10, 1, s5
	v_mov_b32_e32 v255, 0x21000
	v_cmp_eq_u32_e64 s[2:3], 0, v254
	s_nop 1
	v_cndmask_b32_e64 v253, v255, v253, s[2:3]
	ds_read_b128 v[28:31], v250 offset:768
	ds_read_b32 v36, v251 offset:1280
	ds_read_b32 v37, v252 offset:1280
	ds_read_b128 v[24:27], v250 offset:512
	ds_read_b128 v[20:23], v250 offset:256
	ds_read_b128 v[32:35], v250 offset:1024
	ds_read_b128 v[16:19], v250 offset:0
	ds_read_b128 v[50:53], v250 offset:2304
	ds_read_b32 v58, v251 offset:2816
	ds_read_b32 v59, v252 offset:2816
	ds_read_b128 v[46:49], v250 offset:2048
	ds_read_b128 v[42:45], v250 offset:1792
	s_waitcnt lgkmcnt(7)
	v_pk_mul_f32 v[60:61], v[28:29], v[2:3] op_sel:[0,0] op_sel_hi:[0,1]
	v_pk_mul_f32 v[64:65], v[24:25], v[36:37] op_sel:[0,0] op_sel_hi:[0,1]
	v_pk_fma_f32 v[60:61], v[28:29], v[4:5], v[60:61] op_sel:[1,0,0] op_sel_hi:[1,1,1]
	v_pk_mul_f32 v[14:15], v[24:25], v[36:37] op_sel:[1,0] op_sel_hi:[1,1]
	v_pk_fma_f32 v[60:61], v[30:31], v[6:7], v[60:61] op_sel:[0,0,0] op_sel_hi:[0,1,1]
	v_pk_fma_f32 v[2:3], v[20:21], v[2:3], v[64:65] op_sel:[0,0,0] op_sel_hi:[0,1,1]
	v_pk_fma_f32 v[60:61], v[30:31], v[8:9], v[60:61] op_sel:[1,0,0] op_sel_hi:[1,1,1]
	v_pk_fma_f32 v[4:5], v[20:21], v[4:5], v[14:15] op_sel:[1,0,0] op_sel_hi:[1,1,1]
	v_pk_mul_f32 v[64:65], v[26:27], v[36:37] op_sel:[0,0] op_sel_hi:[0,1]
	v_add_f32_dpp v60, v61, v60 quad_perm:[1,0,3,2] row_mask:0xf bank_mask:0xf bound_ctrl:1
	v_pk_mul_f32 v[14:15], v[26:27], v[36:37] op_sel:[1,0] op_sel_hi:[1,1]
	v_pk_fma_f32 v[6:7], v[22:23], v[6:7], v[64:65] op_sel:[0,0,0] op_sel_hi:[0,1,1]
	v_add_f32_dpp v60, v60, v60 quad_perm:[2,3,0,1] row_mask:0xf bank_mask:0xf bound_ctrl:1
	v_pk_fma_f32 v[8:9], v[22:23], v[8:9], v[14:15] op_sel:[1,0,0] op_sel_hi:[1,1,1]
	s_nop 0
	v_add_f32_dpp v60, v60, v60 row_half_mirror row_mask:0xf bank_mask:0xf bound_ctrl:1
	ds_read_b128 v[54:57], v250 offset:2560
	s_nop 0
	v_add_f32_dpp v60, v60, v60 row_mirror row_mask:0xf bank_mask:0xf bound_ctrl:1
	ds_read_b128 v[38:41], v250 offset:1536
	s_nop 0
	v_mov_b32_dpp v61, v60 quad_perm:[1,0,3,2] row_mask:0xf bank_mask:0xf bound_ctrl:1
	s_waitcnt lgkmcnt(7)
	v_pk_fma_f32 v[2:3], v[32:33], v[60:61], v[2:3] op_sel:[0,0,0] op_sel_hi:[0,1,1] neg_lo:[0,1,0] neg_hi:[0,1,0]
	v_pk_fma_f32 v[4:5], v[32:33], v[60:61], v[4:5] op_sel:[1,0,0] op_sel_hi:[1,1,1] neg_lo:[0,1,0] neg_hi:[0,1,0]
	v_pk_fma_f32 v[6:7], v[34:35], v[60:61], v[6:7] op_sel:[0,0,0] op_sel_hi:[0,1,1] neg_lo:[0,1,0] neg_hi:[0,1,0]
	v_pk_fma_f32 v[8:9], v[34:35], v[60:61], v[8:9] op_sel:[1,0,0] op_sel_hi:[1,1,1] neg_lo:[0,1,0] neg_hi:[0,1,0]
	v_pk_mul_f32 v[62:63], v[16:17], v[2:3] op_sel:[0,0] op_sel_hi:[0,1]
	ds_read_b128 v[28:31], v250 offset:3840
	v_pk_fma_f32 v[62:63], v[16:17], v[4:5], v[62:63] op_sel:[1,0,0] op_sel_hi:[1,1,1]
	ds_read_b32 v36, v251 offset:4352
	v_pk_fma_f32 v[62:63], v[18:19], v[6:7], v[62:63] op_sel:[0,0,0] op_sel_hi:[0,1,1]
	ds_read_b32 v37, v252 offset:4352
	v_pk_fma_f32 v[62:63], v[18:19], v[8:9], v[62:63] op_sel:[1,0,0] op_sel_hi:[1,1,1]
	ds_read_b128 v[24:27], v250 offset:3584
	ds_read_b128 v[20:23], v250 offset:3328
	s_waitcnt lgkmcnt(7)
	v_pk_mul_f32 v[60:61], v[50:51], v[2:3] op_sel:[0,0] op_sel_hi:[0,1]
	v_pk_mul_f32 v[64:65], v[46:47], v[58:59] op_sel:[0,0] op_sel_hi:[0,1]
	v_pk_fma_f32 v[60:61], v[50:51], v[4:5], v[60:61] op_sel:[1,0,0] op_sel_hi:[1,1,1]
	v_pk_mul_f32 v[14:15], v[46:47], v[58:59] op_sel:[1,0] op_sel_hi:[1,1]
	v_pk_fma_f32 v[60:61], v[52:53], v[6:7], v[60:61] op_sel:[0,0,0] op_sel_hi:[0,1,1]
	v_pk_fma_f32 v[2:3], v[42:43], v[2:3], v[64:65] op_sel:[0,0,0] op_sel_hi:[0,1,1]
	v_pk_fma_f32 v[60:61], v[52:53], v[8:9], v[60:61] op_sel:[1,0,0] op_sel_hi:[1,1,1]
	v_pk_fma_f32 v[4:5], v[42:43], v[4:5], v[14:15] op_sel:[1,0,0] op_sel_hi:[1,1,1]
	v_pk_mul_f32 v[64:65], v[48:49], v[58:59] op_sel:[0,0] op_sel_hi:[0,1]
	v_add_f32_dpp v60, v61, v60 quad_perm:[1,0,3,2] row_mask:0xf bank_mask:0xf bound_ctrl:1
	v_pk_mul_f32 v[14:15], v[48:49], v[58:59] op_sel:[1,0] op_sel_hi:[1,1]
	v_pk_fma_f32 v[6:7], v[44:45], v[6:7], v[64:65] op_sel:[0,0,0] op_sel_hi:[0,1,1]
	v_add_f32_dpp v60, v60, v60 quad_perm:[2,3,0,1] row_mask:0xf bank_mask:0xf bound_ctrl:1
	v_add_f32_dpp v62, v63, v62 quad_perm:[1,0,3,2] row_mask:0xf bank_mask:0xf bound_ctrl:1
	v_pk_fma_f32 v[8:9], v[44:45], v[8:9], v[14:15] op_sel:[1,0,0] op_sel_hi:[1,1,1]
	v_add_f32_dpp v60, v60, v60 row_half_mirror row_mask:0xf bank_mask:0xf bound_ctrl:1
	v_add_f32_dpp v62, v62, v62 quad_perm:[2,3,0,1] row_mask:0xf bank_mask:0xf bound_ctrl:1
	ds_read_b128 v[32:35], v250 offset:4096
	v_add_f32_dpp v60, v60, v60 row_mirror row_mask:0xf bank_mask:0xf bound_ctrl:1
	v_add_f32_dpp v62, v62, v62 row_half_mirror row_mask:0xf bank_mask:0xf bound_ctrl:1
	ds_read_b128 v[16:19], v250 offset:3072
	v_mov_b32_dpp v61, v60 quad_perm:[1,0,3,2] row_mask:0xf bank_mask:0xf bound_ctrl:1
	v_add_f32_dpp v62, v62, v62 row_mirror row_mask:0xf bank_mask:0xf bound_ctrl:1
	s_waitcnt lgkmcnt(7)
; #define LAS __attribute__((address_space(3)))
; DI unsigned pk2(float a, float b) { f32x2 v = {a, b}; bf2_t r = __builtin_convertvector(v, bf2_t); return __builtin_bit_cast(unsigned, r); }
; DI f32x2 red16p(f32x2 x) { float a = x.x, b = x.y; red16x2(a, b); return (f32x2){a, b}; }
; DI void scan_bh2(const Args& a, int l, int bh, int halfsel, LAS unsigned char* lds) {
;     ...
;             for (int st = 0; st < T; ++st) {
;                 f32x4 nr4, nd4, nk4, nkk4, nb4; f32x2 nv2;
;                 if (st < T - 1) {
;                     const LAS float* o = cur + (st + 1) * 384;
;                     nr4 = *(const LAS f32x4*)(o + kq * 4); nd4 = *(const LAS f32x4*)(o + 64 + kq * 4); nk4 = *(const LAS f32x4*)(o + 128 + kq * 4);
;                     nkk4 = *(const LAS f32x4*)(o + 192 + kq * 4); nb4 = *(const LAS f32x4*)(o + 256 + kq * 4); nv2 = *(const LAS f32x2*)(o + 320 + row0);
;                 }
;                 f32x2 sa = S[0] * kk4[0]; sa += S[1] * kk4[1]; f32x2 sb = S[2] * kk4[2]; sb += S[3] * kk4[3]; sa += sb;
;                 sa = red16p(sa); sa = -sa;
; #pragma unroll
;                 for (int j = 0; j < 4; ++j) S[j] = S[j] * d4[j] + sa * b4[j] + v2 * k4[j];
;                 f32x2 y = S[0] * r4[0]; y += S[1] * r4[1]; f32x2 yc = S[2] * r4[2]; yc += S[3] * r4[3]; y += yc;
;                 y = red16p(y);
;                 *(LAS unsigned*)(yb + st * 128 + row0 * 2) = pk2(y.x, y.y);
	v_pk_fma_f32 v[2:3], v[54:55], v[60:61], v[2:3] op_sel:[0,0,0] op_sel_hi:[0,1,1] neg_lo:[0,1,0] neg_hi:[0,1,0]
	v_pk_fma_f32 v[4:5], v[54:55], v[60:61], v[4:5] op_sel:[1,0,0] op_sel_hi:[1,1,1] neg_lo:[0,1,0] neg_hi:[0,1,0]
	v_mov_b32_dpp v63, v62 quad_perm:[1,0,3,2] row_mask:0xf bank_mask:0xf bound_ctrl:1
	v_pk_fma_f32 v[6:7], v[56:57], v[60:61], v[6:7] op_sel:[0,0,0] op_sel_hi:[0,1,1] neg_lo:[0,1,0] neg_hi:[0,1,0]
	v_cvt_pk_bf16_f32 v64, v62, v63
	v_pk_fma_f32 v[8:9], v[56:57], v[60:61], v[8:9] op_sel:[1,0,0] op_sel_hi:[1,1,1] neg_lo:[0,1,0] neg_hi:[0,1,0]
	ds_write_b32 v253, v64 offset:0
	v_pk_mul_f32 v[62:63], v[38:39], v[2:3] op_sel:[0,0] op_sel_hi:[0,1]
	ds_read_b128 v[50:53], v250 offset:5376
	v_pk_fma_f32 v[62:63], v[38:39], v[4:5], v[62:63] op_sel:[1,0,0] op_sel_hi:[1,1,1]
	ds_read_b32 v58, v251 offset:5888
	v_pk_fma_f32 v[62:63], v[40:41], v[6:7], v[62:63] op_sel:[0,0,0] op_sel_hi:[0,1,1]
	ds_read_b32 v59, v252 offset:5888
	v_pk_fma_f32 v[62:63], v[40:41], v[8:9], v[62:63] op_sel:[1,0,0] op_sel_hi:[1,1,1]
	ds_read_b128 v[46:49], v250 offset:5120
	ds_read_b128 v[42:45], v250 offset:4864
	s_waitcnt lgkmcnt(8)
	v_pk_mul_f32 v[60:61], v[28:29], v[2:3] op_sel:[0,0] op_sel_hi:[0,1]
	v_pk_mul_f32 v[64:65], v[24:25], v[36:37] op_sel:[0,0] op_sel_hi:[0,1]
	v_pk_fma_f32 v[60:61], v[28:29], v[4:5], v[60:61] op_sel:[1,0,0] op_sel_hi:[1,1,1]
	v_pk_mul_f32 v[14:15], v[24:25], v[36:37] op_sel:[1,0] op_sel_hi:[1,1]
	v_pk_fma_f32 v[60:61], v[30:31], v[6:7], v[60:61] op_sel:[0,0,0] op_sel_hi:[0,1,1]
	v_pk_fma_f32 v[2:3], v[20:21], v[2:3], v[64:65] op_sel:[0,0,0] op_sel_hi:[0,1,1]
	v_pk_fma_f32 v[60:61], v[30:31], v[8:9], v[60:61] op_sel:[1,0,0] op_sel_hi:[1,1,1]
	v_pk_fma_f32 v[4:5], v[20:21], v[4:5], v[14:15] op_sel:[1,0,0] op_sel_hi:[1,1,1]
	v_pk_mul_f32 v[64:65], v[26:27], v[36:37] op_sel:[0,0] op_sel_hi:[0,1]
	v_add_f32_dpp v60, v61, v60 quad_perm:[1,0,3,2] row_mask:0xf bank_mask:0xf bound_ctrl:1
	v_pk_mul_f32 v[14:15], v[26:27], v[36:37] op_sel:[1,0] op_sel_hi:[1,1]
	v_pk_fma_f32 v[6:7], v[22:23], v[6:7], v[64:65] op_sel:[0,0,0] op_sel_hi:[0,1,1]
	v_add_f32_dpp v60, v60, v60 quad_perm:[2,3,0,1] row_mask:0xf bank_mask:0xf bound_ctrl:1
	v_add_f32_dpp v62, v63, v62 quad_perm:[1,0,3,2] row_mask:0xf bank_mask:0xf bound_ctrl:1
	v_pk_fma_f32 v[8:9], v[22:23], v[8:9], v[14:15] op_sel:[1,0,0] op_sel_hi:[1,1,1]
	v_add_f32_dpp v60, v60, v60 row_half_mirror row_mask:0xf bank_mask:0xf bound_ctrl:1
	v_add_f32_dpp v62, v62, v62 quad_perm:[2,3,0,1] row_mask:0xf bank_mask:0xf bound_ctrl:1
	ds_read_b128 v[54:57], v250 offset:5632
	v_add_f32_dpp v60, v60, v60 row_mirror row_mask:0xf bank_mask:0xf bound_ctrl:1
	v_add_f32_dpp v62, v62, v62 row_half_mirror row_mask:0xf bank_mask:0xf bound_ctrl:1
	ds_read_b128 v[38:41], v250 offset:4608
	v_mov_b32_dpp v61, v60 quad_perm:[1,0,3,2] row_mask:0xf bank_mask:0xf bound_ctrl:1
	v_add_f32_dpp v62, v62, v62 row_mirror row_mask:0xf bank_mask:0xf bound_ctrl:1
	s_waitcnt lgkmcnt(8)
	v_pk_fma_f32 v[2:3], v[32:33], v[60:61], v[2:3] op_sel:[0,0,0] op_sel_hi:[0,1,1] neg_lo:[0,1,0] neg_hi:[0,1,0]
	v_pk_fma_f32 v[4:5], v[32:33], v[60:61], v[4:5] op_sel:[1,0,0] op_sel_hi:[1,1,1] neg_lo:[0,1,0] neg_hi:[0,1,0]
	v_mov_b32_dpp v63, v62 quad_perm:[1,0,3,2] row_mask:0xf bank_mask:0xf bound_ctrl:1
	v_pk_fma_f32 v[6:7], v[34:35], v[60:61], v[6:7] op_sel:[0,0,0] op_sel_hi:[0,1,1] neg_lo:[0,1,0] neg_hi:[0,1,0]
	v_cvt_pk_bf16_f32 v64, v62, v63
	v_pk_fma_f32 v[8:9], v[34:35], v[60:61], v[8:9] op_sel:[1,0,0] op_sel_hi:[1,1,1] neg_lo:[0,1,0] neg_hi:[0,1,0]
	ds_write_b32 v253, v64 offset:128
	v_pk_mul_f32 v[62:63], v[16:17], v[2:3] op_sel:[0,0] op_sel_hi:[0,1]
	ds_read_b128 v[28:31], v250 offset:6912
	v_pk_fma_f32 v[62:63], v[16:17], v[4:5], v[62:63] op_sel:[1,0,0] op_sel_hi:[1,1,1]
	ds_read_b32 v36, v251 offset:7424
	v_pk_fma_f32 v[62:63], v[18:19], v[6:7], v[62:63] op_sel:[0,0,0] op_sel_hi:[0,1,1]
	ds_read_b32 v37, v252 offset:7424
	v_pk_fma_f32 v[62:63], v[18:19], v[8:9], v[62:63] op_sel:[1,0,0] op_sel_hi:[1,1,1]
	ds_read_b128 v[24:27], v250 offset:6656
	ds_read_b128 v[20:23], v250 offset:6400
	s_waitcnt lgkmcnt(8)
	v_pk_mul_f32 v[60:61], v[50:51], v[2:3] op_sel:[0,0] op_sel_hi:[0,1]
	v_pk_mul_f32 v[64:65], v[46:47], v[58:59] op_sel:[0,0] op_sel_hi:[0,1]
	v_pk_fma_f32 v[60:61], v[50:51], v[4:5], v[60:61] op_sel:[1,0,0] op_sel_hi:[1,1,1]
	v_pk_mul_f32 v[14:15], v[46:47], v[58:59] op_sel:[1,0] op_sel_hi:[1,1]
	v_pk_fma_f32 v[60:61], v[52:53], v[6:7], v[60:61] op_sel:[0,0,0] op_sel_hi:[0,1,1]
	v_pk_fma_f32 v[2:3], v[42:43], v[2:3], v[64:65] op_sel:[0,0,0] op_sel_hi:[0,1,1]
	v_pk_fma_f32 v[60:61], v[52:53], v[8:9], v[60:61] op_sel:[1,0,0] op_sel_hi:[1,1,1]
	v_pk_fma_f32 v[4:5], v[42:43], v[4:5], v[14:15] op_sel:[1,0,0] op_sel_hi:[1,1,1]
	v_pk_mul_f32 v[64:65], v[48:49], v[58:59] op_sel:[0,0] op_sel_hi:[0,1]
	v_add_f32_dpp v60, v61, v60 quad_perm:[1,0,3,2] row_mask:0xf bank_mask:0xf bound_ctrl:1
	v_pk_mul_f32 v[14:15], v[48:49], v[58:59] op_sel:[1,0] op_sel_hi:[1,1]
	v_pk_fma_f32 v[6:7], v[44:45], v[6:7], v[64:65] op_sel:[0,0,0] op_sel_hi:[0,1,1]
	v_add_f32_dpp v60, v60, v60 quad_perm:[2,3,0,1] row_mask:0xf bank_mask:0xf bound_ctrl:1
	v_add_f32_dpp v62, v63, v62 quad_perm:[1,0,3,2] row_mask:0xf bank_mask:0xf bound_ctrl:1
	v_pk_fma_f32 v[8:9], v[44:45], v[8:9], v[14:15] op_sel:[1,0,0] op_sel_hi:[1,1,1]
	v_add_f32_dpp v60, v60, v60 row_half_mirror row_mask:0xf bank_mask:0xf bound_ctrl:1
	v_add_f32_dpp v62, v62, v62 quad_perm:[2,3,0,1] row_mask:0xf bank_mask:0xf bound_ctrl:1
	ds_read_b128 v[32:35], v250 offset:7168
	v_add_f32_dpp v60, v60, v60 row_mirror row_mask:0xf bank_mask:0xf bound_ctrl:1
	v_add_f32_dpp v62, v62, v62 row_half_mirror row_mask:0xf bank_mask:0xf bound_ctrl:1
	ds_read_b128 v[16:19], v250 offset:6144
	v_mov_b32_dpp v61, v60 quad_perm:[1,0,3,2] row_mask:0xf bank_mask:0xf bound_ctrl:1
	v_add_f32_dpp v62, v62, v62 row_mirror row_mask:0xf bank_mask:0xf bound_ctrl:1
	s_waitcnt lgkmcnt(8)
; #define LAS __attribute__((address_space(3)))
; DI unsigned pk2(float a, float b) { f32x2 v = {a, b}; bf2_t r = __builtin_convertvector(v, bf2_t); return __builtin_bit_cast(unsigned, r); }
; DI f32x2 red16p(f32x2 x) { float a = x.x, b = x.y; red16x2(a, b); return (f32x2){a, b}; }
; DI void scan_bh2(const Args& a, int l, int bh, int halfsel, LAS unsigned char* lds) {
;     ...
;             for (int st = 0; st < T; ++st) {
;                 f32x4 nr4, nd4, nk4, nkk4, nb4; f32x2 nv2;
;                 if (st < T - 1) {
;                     const LAS float* o = cur + (st + 1) * 384;
;                     nr4 = *(const LAS f32x4*)(o + kq * 4); nd4 = *(const LAS f32x4*)(o + 64 + kq * 4); nk4 = *(const LAS f32x4*)(o + 128 + kq * 4);
;                     nkk4 = *(const LAS f32x4*)(o + 192 + kq * 4); nb4 = *(const LAS f32x4*)(o + 256 + kq * 4); nv2 = *(const LAS f32x2*)(o + 320 + row0);
;                 }
;                 f32x2 sa = S[0] * kk4[0]; sa += S[1] * kk4[1]; f32x2 sb = S[2] * kk4[2]; sb += S[3] * kk4[3]; sa += sb;
;                 sa = red16p(sa); sa = -sa;
; #pragma unroll
;                 for (int j = 0; j < 4; ++j) S[j] = S[j] * d4[j] + sa * b4[j] + v2 * k4[j];
;                 f32x2 y = S[0] * r4[0]; y += S[1] * r4[1]; f32x2 yc = S[2] * r4[2]; yc += S[3] * r4[3]; y += yc;
;                 y = red16p(y);
;                 *(LAS unsigned*)(yb + st * 128 + row0 * 2) = pk2(y.x, y.y);
	v_pk_fma_f32 v[2:3], v[54:55], v[60:61], v[2:3] op_sel:[0,0,0] op_sel_hi:[0,1,1] neg_lo:[0,1,0] neg_hi:[0,1,0]
	v_pk_fma_f32 v[4:5], v[54:55], v[60:61], v[4:5] op_sel:[1,0,0] op_sel_hi:[1,1,1] neg_lo:[0,1,0] neg_hi:[0,1,0]
	v_mov_b32_dpp v63, v62 quad_perm:[1,0,3,2] row_mask:0xf bank_mask:0xf bound_ctrl:1
	v_pk_fma_f32 v[6:7], v[56:57], v[60:61], v[6:7] op_sel:[0,0,0] op_sel_hi:[0,1,1] neg_lo:[0,1,0] neg_hi:[0,1,0]
	v_cvt_pk_bf16_f32 v64, v62, v63
	v_pk_fma_f32 v[8:9], v[56:57], v[60:61], v[8:9] op_sel:[1,0,0] op_sel_hi:[1,1,1] neg_lo:[0,1,0] neg_hi:[0,1,0]
	ds_write_b32 v253, v64 offset:256
	v_pk_mul_f32 v[62:63], v[38:39], v[2:3] op_sel:[0,0] op_sel_hi:[0,1]
	ds_read_b128 v[50:53], v250 offset:8448
	v_pk_fma_f32 v[62:63], v[38:39], v[4:5], v[62:63] op_sel:[1,0,0] op_sel_hi:[1,1,1]
	ds_read_b32 v58, v251 offset:8960
	v_pk_fma_f32 v[62:63], v[40:41], v[6:7], v[62:63] op_sel:[0,0,0] op_sel_hi:[0,1,1]
	ds_read_b32 v59, v252 offset:8960
	v_pk_fma_f32 v[62:63], v[40:41], v[8:9], v[62:63] op_sel:[1,0,0] op_sel_hi:[1,1,1]
	ds_read_b128 v[46:49], v250 offset:8192
	ds_read_b128 v[42:45], v250 offset:7936
	s_waitcnt lgkmcnt(8)
	v_pk_mul_f32 v[60:61], v[28:29], v[2:3] op_sel:[0,0] op_sel_hi:[0,1]
	v_pk_mul_f32 v[64:65], v[24:25], v[36:37] op_sel:[0,0] op_sel_hi:[0,1]
	v_pk_fma_f32 v[60:61], v[28:29], v[4:5], v[60:61] op_sel:[1,0,0] op_sel_hi:[1,1,1]
	v_pk_mul_f32 v[14:15], v[24:25], v[36:37] op_sel:[1,0] op_sel_hi:[1,1]
	v_pk_fma_f32 v[60:61], v[30:31], v[6:7], v[60:61] op_sel:[0,0,0] op_sel_hi:[0,1,1]
	v_pk_fma_f32 v[2:3], v[20:21], v[2:3], v[64:65] op_sel:[0,0,0] op_sel_hi:[0,1,1]
	v_pk_fma_f32 v[60:61], v[30:31], v[8:9], v[60:61] op_sel:[1,0,0] op_sel_hi:[1,1,1]
	v_pk_fma_f32 v[4:5], v[20:21], v[4:5], v[14:15] op_sel:[1,0,0] op_sel_hi:[1,1,1]
	v_pk_mul_f32 v[64:65], v[26:27], v[36:37] op_sel:[0,0] op_sel_hi:[0,1]
	v_add_f32_dpp v60, v61, v60 quad_perm:[1,0,3,2] row_mask:0xf bank_mask:0xf bound_ctrl:1
	v_pk_mul_f32 v[14:15], v[26:27], v[36:37] op_sel:[1,0] op_sel_hi:[1,1]
	v_pk_fma_f32 v[6:7], v[22:23], v[6:7], v[64:65] op_sel:[0,0,0] op_sel_hi:[0,1,1]
	v_add_f32_dpp v60, v60, v60 quad_perm:[2,3,0,1] row_mask:0xf bank_mask:0xf bound_ctrl:1
	v_add_f32_dpp v62, v63, v62 quad_perm:[1,0,3,2] row_mask:0xf bank_mask:0xf bound_ctrl:1
	v_pk_fma_f32 v[8:9], v[22:23], v[8:9], v[14:15] op_sel:[1,0,0] op_sel_hi:[1,1,1]
	v_add_f32_dpp v60, v60, v60 row_half_mirror row_mask:0xf bank_mask:0xf bound_ctrl:1
	v_add_f32_dpp v62, v62, v62 quad_perm:[2,3,0,1] row_mask:0xf bank_mask:0xf bound_ctrl:1
	ds_read_b128 v[54:57], v250 offset:8704
	v_add_f32_dpp v60, v60, v60 row_mirror row_mask:0xf bank_mask:0xf bound_ctrl:1
	v_add_f32_dpp v62, v62, v62 row_half_mirror row_mask:0xf bank_mask:0xf bound_ctrl:1
	ds_read_b128 v[38:41], v250 offset:7680
	v_mov_b32_dpp v61, v60 quad_perm:[1,0,3,2] row_mask:0xf bank_mask:0xf bound_ctrl:1
	v_add_f32_dpp v62, v62, v62 row_mirror row_mask:0xf bank_mask:0xf bound_ctrl:1
	s_waitcnt lgkmcnt(8)
	v_pk_fma_f32 v[2:3], v[32:33], v[60:61], v[2:3] op_sel:[0,0,0] op_sel_hi:[0,1,1] neg_lo:[0,1,0] neg_hi:[0,1,0]
	v_pk_fma_f32 v[4:5], v[32:33], v[60:61], v[4:5] op_sel:[1,0,0] op_sel_hi:[1,1,1] neg_lo:[0,1,0] neg_hi:[0,1,0]
	v_mov_b32_dpp v63, v62 quad_perm:[1,0,3,2] row_mask:0xf bank_mask:0xf bound_ctrl:1
	v_pk_fma_f32 v[6:7], v[34:35], v[60:61], v[6:7] op_sel:[0,0,0] op_sel_hi:[0,1,1] neg_lo:[0,1,0] neg_hi:[0,1,0]
	v_cvt_pk_bf16_f32 v64, v62, v63
	v_pk_fma_f32 v[8:9], v[34:35], v[60:61], v[8:9] op_sel:[1,0,0] op_sel_hi:[1,1,1] neg_lo:[0,1,0] neg_hi:[0,1,0]
	ds_write_b32 v253, v64 offset:384
	v_pk_mul_f32 v[62:63], v[16:17], v[2:3] op_sel:[0,0] op_sel_hi:[0,1]
	ds_read_b128 v[28:31], v250 offset:9984
	v_pk_fma_f32 v[62:63], v[16:17], v[4:5], v[62:63] op_sel:[1,0,0] op_sel_hi:[1,1,1]
	ds_read_b32 v36, v251 offset:10496
	v_pk_fma_f32 v[62:63], v[18:19], v[6:7], v[62:63] op_sel:[0,0,0] op_sel_hi:[0,1,1]
	ds_read_b32 v37, v252 offset:10496
	v_pk_fma_f32 v[62:63], v[18:19], v[8:9], v[62:63] op_sel:[1,0,0] op_sel_hi:[1,1,1]
	ds_read_b128 v[24:27], v250 offset:9728
	ds_read_b128 v[20:23], v250 offset:9472
	s_waitcnt lgkmcnt(8)
	v_pk_mul_f32 v[60:61], v[50:51], v[2:3] op_sel:[0,0] op_sel_hi:[0,1]
	v_pk_mul_f32 v[64:65], v[46:47], v[58:59] op_sel:[0,0] op_sel_hi:[0,1]
	v_pk_fma_f32 v[60:61], v[50:51], v[4:5], v[60:61] op_sel:[1,0,0] op_sel_hi:[1,1,1]
	v_pk_mul_f32 v[14:15], v[46:47], v[58:59] op_sel:[1,0] op_sel_hi:[1,1]
	v_pk_fma_f32 v[60:61], v[52:53], v[6:7], v[60:61] op_sel:[0,0,0] op_sel_hi:[0,1,1]
	v_pk_fma_f32 v[2:3], v[42:43], v[2:3], v[64:65] op_sel:[0,0,0] op_sel_hi:[0,1,1]
	v_pk_fma_f32 v[60:61], v[52:53], v[8:9], v[60:61] op_sel:[1,0,0] op_sel_hi:[1,1,1]
	v_pk_fma_f32 v[4:5], v[42:43], v[4:5], v[14:15] op_sel:[1,0,0] op_sel_hi:[1,1,1]
	v_pk_mul_f32 v[64:65], v[48:49], v[58:59] op_sel:[0,0] op_sel_hi:[0,1]
	v_add_f32_dpp v60, v61, v60 quad_perm:[1,0,3,2] row_mask:0xf bank_mask:0xf bound_ctrl:1
	v_pk_mul_f32 v[14:15], v[48:49], v[58:59] op_sel:[1,0] op_sel_hi:[1,1]
	v_pk_fma_f32 v[6:7], v[44:45], v[6:7], v[64:65] op_sel:[0,0,0] op_sel_hi:[0,1,1]
	v_add_f32_dpp v60, v60, v60 quad_perm:[2,3,0,1] row_mask:0xf bank_mask:0xf bound_ctrl:1
	v_add_f32_dpp v62, v63, v62 quad_perm:[1,0,3,2] row_mask:0xf bank_mask:0xf bound_ctrl:1
	v_pk_fma_f32 v[8:9], v[44:45], v[8:9], v[14:15] op_sel:[1,0,0] op_sel_hi:[1,1,1]
	v_add_f32_dpp v60, v60, v60 row_half_mirror row_mask:0xf bank_mask:0xf bound_ctrl:1
	v_add_f32_dpp v62, v62, v62 quad_perm:[2,3,0,1] row_mask:0xf bank_mask:0xf bound_ctrl:1
	ds_read_b128 v[32:35], v250 offset:10240
	v_add_f32_dpp v60, v60, v60 row_mirror row_mask:0xf bank_mask:0xf bound_ctrl:1
	v_add_f32_dpp v62, v62, v62 row_half_mirror row_mask:0xf bank_mask:0xf bound_ctrl:1
	ds_read_b128 v[16:19], v250 offset:9216
	v_mov_b32_dpp v61, v60 quad_perm:[1,0,3,2] row_mask:0xf bank_mask:0xf bound_ctrl:1
	v_add_f32_dpp v62, v62, v62 row_mirror row_mask:0xf bank_mask:0xf bound_ctrl:1
	s_waitcnt lgkmcnt(8)
; #define LAS __attribute__((address_space(3)))
; DI unsigned pk2(float a, float b) { f32x2 v = {a, b}; bf2_t r = __builtin_convertvector(v, bf2_t); return __builtin_bit_cast(unsigned, r); }
; DI f32x2 red16p(f32x2 x) { float a = x.x, b = x.y; red16x2(a, b); return (f32x2){a, b}; }
; DI void scan_bh2(const Args& a, int l, int bh, int halfsel, LAS unsigned char* lds) {
;     ...
;             for (int st = 0; st < T; ++st) {
;                 f32x4 nr4, nd4, nk4, nkk4, nb4; f32x2 nv2;
;                 if (st < T - 1) {
;                     const LAS float* o = cur + (st + 1) * 384;
;                     nr4 = *(const LAS f32x4*)(o + kq * 4); nd4 = *(const LAS f32x4*)(o + 64 + kq * 4); nk4 = *(const LAS f32x4*)(o + 128 + kq * 4);
;                     nkk4 = *(const LAS f32x4*)(o + 192 + kq * 4); nb4 = *(const LAS f32x4*)(o + 256 + kq * 4); nv2 = *(const LAS f32x2*)(o + 320 + row0);
;                 }
;                 f32x2 sa = S[0] * kk4[0]; sa += S[1] * kk4[1]; f32x2 sb = S[2] * kk4[2]; sb += S[3] * kk4[3]; sa += sb;
;                 sa = red16p(sa); sa = -sa;
; #pragma unroll
;                 for (int j = 0; j < 4; ++j) S[j] = S[j] * d4[j] + sa * b4[j] + v2 * k4[j];
;                 f32x2 y = S[0] * r4[0]; y += S[1] * r4[1]; f32x2 yc = S[2] * r4[2]; yc += S[3] * r4[3]; y += yc;
;                 y = red16p(y);
;                 *(LAS unsigned*)(yb + st * 128 + row0 * 2) = pk2(y.x, y.y);
	v_pk_fma_f32 v[2:3], v[54:55], v[60:61], v[2:3] op_sel:[0,0,0] op_sel_hi:[0,1,1] neg_lo:[0,1,0] neg_hi:[0,1,0]
	v_pk_fma_f32 v[4:5], v[54:55], v[60:61], v[4:5] op_sel:[1,0,0] op_sel_hi:[1,1,1] neg_lo:[0,1,0] neg_hi:[0,1,0]
	v_mov_b32_dpp v63, v62 quad_perm:[1,0,3,2] row_mask:0xf bank_mask:0xf bound_ctrl:1
	v_pk_fma_f32 v[6:7], v[56:57], v[60:61], v[6:7] op_sel:[0,0,0] op_sel_hi:[0,1,1] neg_lo:[0,1,0] neg_hi:[0,1,0]
	v_cvt_pk_bf16_f32 v64, v62, v63
	v_pk_fma_f32 v[8:9], v[56:57], v[60:61], v[8:9] op_sel:[1,0,0] op_sel_hi:[1,1,1] neg_lo:[0,1,0] neg_hi:[0,1,0]
	ds_write_b32 v253, v64 offset:512
	v_pk_mul_f32 v[62:63], v[38:39], v[2:3] op_sel:[0,0] op_sel_hi:[0,1]
	ds_read_b128 v[50:53], v250 offset:11520
	v_pk_fma_f32 v[62:63], v[38:39], v[4:5], v[62:63] op_sel:[1,0,0] op_sel_hi:[1,1,1]
	ds_read_b32 v58, v251 offset:12032
	v_pk_fma_f32 v[62:63], v[40:41], v[6:7], v[62:63] op_sel:[0,0,0] op_sel_hi:[0,1,1]
	ds_read_b32 v59, v252 offset:12032
	v_pk_fma_f32 v[62:63], v[40:41], v[8:9], v[62:63] op_sel:[1,0,0] op_sel_hi:[1,1,1]
	ds_read_b128 v[46:49], v250 offset:11264
	ds_read_b128 v[42:45], v250 offset:11008
	s_waitcnt lgkmcnt(8)
	v_pk_mul_f32 v[60:61], v[28:29], v[2:3] op_sel:[0,0] op_sel_hi:[0,1]
	v_pk_mul_f32 v[64:65], v[24:25], v[36:37] op_sel:[0,0] op_sel_hi:[0,1]
	v_pk_fma_f32 v[60:61], v[28:29], v[4:5], v[60:61] op_sel:[1,0,0] op_sel_hi:[1,1,1]
	v_pk_mul_f32 v[14:15], v[24:25], v[36:37] op_sel:[1,0] op_sel_hi:[1,1]
	v_pk_fma_f32 v[60:61], v[30:31], v[6:7], v[60:61] op_sel:[0,0,0] op_sel_hi:[0,1,1]
	v_pk_fma_f32 v[2:3], v[20:21], v[2:3], v[64:65] op_sel:[0,0,0] op_sel_hi:[0,1,1]
	v_pk_fma_f32 v[60:61], v[30:31], v[8:9], v[60:61] op_sel:[1,0,0] op_sel_hi:[1,1,1]
	v_pk_fma_f32 v[4:5], v[20:21], v[4:5], v[14:15] op_sel:[1,0,0] op_sel_hi:[1,1,1]
	v_pk_mul_f32 v[64:65], v[26:27], v[36:37] op_sel:[0,0] op_sel_hi:[0,1]
	v_add_f32_dpp v60, v61, v60 quad_perm:[1,0,3,2] row_mask:0xf bank_mask:0xf bound_ctrl:1
	v_pk_mul_f32 v[14:15], v[26:27], v[36:37] op_sel:[1,0] op_sel_hi:[1,1]
	v_pk_fma_f32 v[6:7], v[22:23], v[6:7], v[64:65] op_sel:[0,0,0] op_sel_hi:[0,1,1]
	v_add_f32_dpp v60, v60, v60 quad_perm:[2,3,0,1] row_mask:0xf bank_mask:0xf bound_ctrl:1
	v_add_f32_dpp v62, v63, v62 quad_perm:[1,0,3,2] row_mask:0xf bank_mask:0xf bound_ctrl:1
	v_pk_fma_f32 v[8:9], v[22:23], v[8:9], v[14:15] op_sel:[1,0,0] op_sel_hi:[1,1,1]
	v_add_f32_dpp v60, v60, v60 row_half_mirror row_mask:0xf bank_mask:0xf bound_ctrl:1
	v_add_f32_dpp v62, v62, v62 quad_perm:[2,3,0,1] row_mask:0xf bank_mask:0xf bound_ctrl:1
	ds_read_b128 v[54:57], v250 offset:11776
	v_add_f32_dpp v60, v60, v60 row_mirror row_mask:0xf bank_mask:0xf bound_ctrl:1
	v_add_f32_dpp v62, v62, v62 row_half_mirror row_mask:0xf bank_mask:0xf bound_ctrl:1
	ds_read_b128 v[38:41], v250 offset:10752
	v_mov_b32_dpp v61, v60 quad_perm:[1,0,3,2] row_mask:0xf bank_mask:0xf bound_ctrl:1
	v_add_f32_dpp v62, v62, v62 row_mirror row_mask:0xf bank_mask:0xf bound_ctrl:1
	s_waitcnt lgkmcnt(8)
	v_pk_fma_f32 v[2:3], v[32:33], v[60:61], v[2:3] op_sel:[0,0,0] op_sel_hi:[0,1,1] neg_lo:[0,1,0] neg_hi:[0,1,0]
	v_pk_fma_f32 v[4:5], v[32:33], v[60:61], v[4:5] op_sel:[1,0,0] op_sel_hi:[1,1,1] neg_lo:[0,1,0] neg_hi:[0,1,0]
	v_mov_b32_dpp v63, v62 quad_perm:[1,0,3,2] row_mask:0xf bank_mask:0xf bound_ctrl:1
	v_pk_fma_f32 v[6:7], v[34:35], v[60:61], v[6:7] op_sel:[0,0,0] op_sel_hi:[0,1,1] neg_lo:[0,1,0] neg_hi:[0,1,0]
	v_cvt_pk_bf16_f32 v64, v62, v63
	v_pk_fma_f32 v[8:9], v[34:35], v[60:61], v[8:9] op_sel:[1,0,0] op_sel_hi:[1,1,1] neg_lo:[0,1,0] neg_hi:[0,1,0]
	ds_write_b32 v253, v64 offset:640
	v_pk_mul_f32 v[62:63], v[16:17], v[2:3] op_sel:[0,0] op_sel_hi:[0,1]
	ds_read_b128 v[28:31], v250 offset:13056
	v_pk_fma_f32 v[62:63], v[16:17], v[4:5], v[62:63] op_sel:[1,0,0] op_sel_hi:[1,1,1]
	ds_read_b32 v36, v251 offset:13568
	v_pk_fma_f32 v[62:63], v[18:19], v[6:7], v[62:63] op_sel:[0,0,0] op_sel_hi:[0,1,1]
	ds_read_b32 v37, v252 offset:13568
	v_pk_fma_f32 v[62:63], v[18:19], v[8:9], v[62:63] op_sel:[1,0,0] op_sel_hi:[1,1,1]
	ds_read_b128 v[24:27], v250 offset:12800
	ds_read_b128 v[20:23], v250 offset:12544
	s_waitcnt lgkmcnt(8)
	v_pk_mul_f32 v[60:61], v[50:51], v[2:3] op_sel:[0,0] op_sel_hi:[0,1]
	v_pk_mul_f32 v[64:65], v[46:47], v[58:59] op_sel:[0,0] op_sel_hi:[0,1]
	v_pk_fma_f32 v[60:61], v[50:51], v[4:5], v[60:61] op_sel:[1,0,0] op_sel_hi:[1,1,1]
	v_pk_mul_f32 v[14:15], v[46:47], v[58:59] op_sel:[1,0] op_sel_hi:[1,1]
	v_pk_fma_f32 v[60:61], v[52:53], v[6:7], v[60:61] op_sel:[0,0,0] op_sel_hi:[0,1,1]
	v_pk_fma_f32 v[2:3], v[42:43], v[2:3], v[64:65] op_sel:[0,0,0] op_sel_hi:[0,1,1]
	v_pk_fma_f32 v[60:61], v[52:53], v[8:9], v[60:61] op_sel:[1,0,0] op_sel_hi:[1,1,1]
	v_pk_fma_f32 v[4:5], v[42:43], v[4:5], v[14:15] op_sel:[1,0,0] op_sel_hi:[1,1,1]
	v_pk_mul_f32 v[64:65], v[48:49], v[58:59] op_sel:[0,0] op_sel_hi:[0,1]
	v_add_f32_dpp v60, v61, v60 quad_perm:[1,0,3,2] row_mask:0xf bank_mask:0xf bound_ctrl:1
	v_pk_mul_f32 v[14:15], v[48:49], v[58:59] op_sel:[1,0] op_sel_hi:[1,1]
	v_pk_fma_f32 v[6:7], v[44:45], v[6:7], v[64:65] op_sel:[0,0,0] op_sel_hi:[0,1,1]
	v_add_f32_dpp v60, v60, v60 quad_perm:[2,3,0,1] row_mask:0xf bank_mask:0xf bound_ctrl:1
	v_add_f32_dpp v62, v63, v62 quad_perm:[1,0,3,2] row_mask:0xf bank_mask:0xf bound_ctrl:1
	v_pk_fma_f32 v[8:9], v[44:45], v[8:9], v[14:15] op_sel:[1,0,0] op_sel_hi:[1,1,1]
	v_add_f32_dpp v60, v60, v60 row_half_mirror row_mask:0xf bank_mask:0xf bound_ctrl:1
	v_add_f32_dpp v62, v62, v62 quad_perm:[2,3,0,1] row_mask:0xf bank_mask:0xf bound_ctrl:1
	ds_read_b128 v[32:35], v250 offset:13312
	v_add_f32_dpp v60, v60, v60 row_mirror row_mask:0xf bank_mask:0xf bound_ctrl:1
	v_add_f32_dpp v62, v62, v62 row_half_mirror row_mask:0xf bank_mask:0xf bound_ctrl:1
	ds_read_b128 v[16:19], v250 offset:12288
	v_mov_b32_dpp v61, v60 quad_perm:[1,0,3,2] row_mask:0xf bank_mask:0xf bound_ctrl:1
	v_add_f32_dpp v62, v62, v62 row_mirror row_mask:0xf bank_mask:0xf bound_ctrl:1
	s_waitcnt lgkmcnt(8)
; #define LAS __attribute__((address_space(3)))
; DI unsigned pk2(float a, float b) { f32x2 v = {a, b}; bf2_t r = __builtin_convertvector(v, bf2_t); return __builtin_bit_cast(unsigned, r); }
; DI f32x2 red16p(f32x2 x) { float a = x.x, b = x.y; red16x2(a, b); return (f32x2){a, b}; }
; DI void scan_bh2(const Args& a, int l, int bh, int halfsel, LAS unsigned char* lds) {
;     ...
;             for (int st = 0; st < T; ++st) {
;                 f32x4 nr4, nd4, nk4, nkk4, nb4; f32x2 nv2;
;                 if (st < T - 1) {
;                     const LAS float* o = cur + (st + 1) * 384;
;                     nr4 = *(const LAS f32x4*)(o + kq * 4); nd4 = *(const LAS f32x4*)(o + 64 + kq * 4); nk4 = *(const LAS f32x4*)(o + 128 + kq * 4);
;                     nkk4 = *(const LAS f32x4*)(o + 192 + kq * 4); nb4 = *(const LAS f32x4*)(o + 256 + kq * 4); nv2 = *(const LAS f32x2*)(o + 320 + row0);
;                 }
;                 f32x2 sa = S[0] * kk4[0]; sa += S[1] * kk4[1]; f32x2 sb = S[2] * kk4[2]; sb += S[3] * kk4[3]; sa += sb;
;                 sa = red16p(sa); sa = -sa;
; #pragma unroll
;                 for (int j = 0; j < 4; ++j) S[j] = S[j] * d4[j] + sa * b4[j] + v2 * k4[j];
;                 f32x2 y = S[0] * r4[0]; y += S[1] * r4[1]; f32x2 yc = S[2] * r4[2]; yc += S[3] * r4[3]; y += yc;
;                 y = red16p(y);
;                 *(LAS unsigned*)(yb + st * 128 + row0 * 2) = pk2(y.x, y.y);
	v_pk_fma_f32 v[2:3], v[54:55], v[60:61], v[2:3] op_sel:[0,0,0] op_sel_hi:[0,1,1] neg_lo:[0,1,0] neg_hi:[0,1,0]
	v_pk_fma_f32 v[4:5], v[54:55], v[60:61], v[4:5] op_sel:[1,0,0] op_sel_hi:[1,1,1] neg_lo:[0,1,0] neg_hi:[0,1,0]
	v_mov_b32_dpp v63, v62 quad_perm:[1,0,3,2] row_mask:0xf bank_mask:0xf bound_ctrl:1
	v_pk_fma_f32 v[6:7], v[56:57], v[60:61], v[6:7] op_sel:[0,0,0] op_sel_hi:[0,1,1] neg_lo:[0,1,0] neg_hi:[0,1,0]
	v_cvt_pk_bf16_f32 v64, v62, v63
	v_pk_fma_f32 v[8:9], v[56:57], v[60:61], v[8:9] op_sel:[1,0,0] op_sel_hi:[1,1,1] neg_lo:[0,1,0] neg_hi:[0,1,0]
	ds_write_b32 v253, v64 offset:768
	v_pk_mul_f32 v[62:63], v[38:39], v[2:3] op_sel:[0,0] op_sel_hi:[0,1]
	ds_read_b128 v[50:53], v250 offset:14592
	v_pk_fma_f32 v[62:63], v[38:39], v[4:5], v[62:63] op_sel:[1,0,0] op_sel_hi:[1,1,1]
	ds_read_b32 v58, v251 offset:15104
	v_pk_fma_f32 v[62:63], v[40:41], v[6:7], v[62:63] op_sel:[0,0,0] op_sel_hi:[0,1,1]
	ds_read_b32 v59, v252 offset:15104
	v_pk_fma_f32 v[62:63], v[40:41], v[8:9], v[62:63] op_sel:[1,0,0] op_sel_hi:[1,1,1]
	ds_read_b128 v[46:49], v250 offset:14336
	ds_read_b128 v[42:45], v250 offset:14080
	s_waitcnt lgkmcnt(8)
	v_pk_mul_f32 v[60:61], v[28:29], v[2:3] op_sel:[0,0] op_sel_hi:[0,1]
	v_pk_mul_f32 v[64:65], v[24:25], v[36:37] op_sel:[0,0] op_sel_hi:[0,1]
	v_pk_fma_f32 v[60:61], v[28:29], v[4:5], v[60:61] op_sel:[1,0,0] op_sel_hi:[1,1,1]
	v_pk_mul_f32 v[14:15], v[24:25], v[36:37] op_sel:[1,0] op_sel_hi:[1,1]
	v_pk_fma_f32 v[60:61], v[30:31], v[6:7], v[60:61] op_sel:[0,0,0] op_sel_hi:[0,1,1]
	v_pk_fma_f32 v[2:3], v[20:21], v[2:3], v[64:65] op_sel:[0,0,0] op_sel_hi:[0,1,1]
	v_pk_fma_f32 v[60:61], v[30:31], v[8:9], v[60:61] op_sel:[1,0,0] op_sel_hi:[1,1,1]
	v_pk_fma_f32 v[4:5], v[20:21], v[4:5], v[14:15] op_sel:[1,0,0] op_sel_hi:[1,1,1]
	v_pk_mul_f32 v[64:65], v[26:27], v[36:37] op_sel:[0,0] op_sel_hi:[0,1]
	v_add_f32_dpp v60, v61, v60 quad_perm:[1,0,3,2] row_mask:0xf bank_mask:0xf bound_ctrl:1
	v_pk_mul_f32 v[14:15], v[26:27], v[36:37] op_sel:[1,0] op_sel_hi:[1,1]
	v_pk_fma_f32 v[6:7], v[22:23], v[6:7], v[64:65] op_sel:[0,0,0] op_sel_hi:[0,1,1]
	v_add_f32_dpp v60, v60, v60 quad_perm:[2,3,0,1] row_mask:0xf bank_mask:0xf bound_ctrl:1
	v_add_f32_dpp v62, v63, v62 quad_perm:[1,0,3,2] row_mask:0xf bank_mask:0xf bound_ctrl:1
	v_pk_fma_f32 v[8:9], v[22:23], v[8:9], v[14:15] op_sel:[1,0,0] op_sel_hi:[1,1,1]
	v_add_f32_dpp v60, v60, v60 row_half_mirror row_mask:0xf bank_mask:0xf bound_ctrl:1
	v_add_f32_dpp v62, v62, v62 quad_perm:[2,3,0,1] row_mask:0xf bank_mask:0xf bound_ctrl:1
	ds_read_b128 v[54:57], v250 offset:14848
	v_add_f32_dpp v60, v60, v60 row_mirror row_mask:0xf bank_mask:0xf bound_ctrl:1
	v_add_f32_dpp v62, v62, v62 row_half_mirror row_mask:0xf bank_mask:0xf bound_ctrl:1
	ds_read_b128 v[38:41], v250 offset:13824
	v_mov_b32_dpp v61, v60 quad_perm:[1,0,3,2] row_mask:0xf bank_mask:0xf bound_ctrl:1
	v_add_f32_dpp v62, v62, v62 row_mirror row_mask:0xf bank_mask:0xf bound_ctrl:1
	s_waitcnt lgkmcnt(8)
	v_pk_fma_f32 v[2:3], v[32:33], v[60:61], v[2:3] op_sel:[0,0,0] op_sel_hi:[0,1,1] neg_lo:[0,1,0] neg_hi:[0,1,0]
	v_pk_fma_f32 v[4:5], v[32:33], v[60:61], v[4:5] op_sel:[1,0,0] op_sel_hi:[1,1,1] neg_lo:[0,1,0] neg_hi:[0,1,0]
	v_mov_b32_dpp v63, v62 quad_perm:[1,0,3,2] row_mask:0xf bank_mask:0xf bound_ctrl:1
	v_pk_fma_f32 v[6:7], v[34:35], v[60:61], v[6:7] op_sel:[0,0,0] op_sel_hi:[0,1,1] neg_lo:[0,1,0] neg_hi:[0,1,0]
	v_cvt_pk_bf16_f32 v64, v62, v63
	v_pk_fma_f32 v[8:9], v[34:35], v[60:61], v[8:9] op_sel:[1,0,0] op_sel_hi:[1,1,1] neg_lo:[0,1,0] neg_hi:[0,1,0]
	ds_write_b32 v253, v64 offset:896
	v_pk_mul_f32 v[62:63], v[16:17], v[2:3] op_sel:[0,0] op_sel_hi:[0,1]
	ds_read_b128 v[28:31], v250 offset:16128
	v_pk_fma_f32 v[62:63], v[16:17], v[4:5], v[62:63] op_sel:[1,0,0] op_sel_hi:[1,1,1]
	ds_read_b32 v36, v251 offset:16640
	v_pk_fma_f32 v[62:63], v[18:19], v[6:7], v[62:63] op_sel:[0,0,0] op_sel_hi:[0,1,1]
	ds_read_b32 v37, v252 offset:16640
	v_pk_fma_f32 v[62:63], v[18:19], v[8:9], v[62:63] op_sel:[1,0,0] op_sel_hi:[1,1,1]
	ds_read_b128 v[24:27], v250 offset:15872
	ds_read_b128 v[20:23], v250 offset:15616
	s_waitcnt lgkmcnt(8)
	v_pk_mul_f32 v[60:61], v[50:51], v[2:3] op_sel:[0,0] op_sel_hi:[0,1]
	v_pk_mul_f32 v[64:65], v[46:47], v[58:59] op_sel:[0,0] op_sel_hi:[0,1]
	v_pk_fma_f32 v[60:61], v[50:51], v[4:5], v[60:61] op_sel:[1,0,0] op_sel_hi:[1,1,1]
	v_pk_mul_f32 v[14:15], v[46:47], v[58:59] op_sel:[1,0] op_sel_hi:[1,1]
	v_pk_fma_f32 v[60:61], v[52:53], v[6:7], v[60:61] op_sel:[0,0,0] op_sel_hi:[0,1,1]
	v_pk_fma_f32 v[2:3], v[42:43], v[2:3], v[64:65] op_sel:[0,0,0] op_sel_hi:[0,1,1]
	v_pk_fma_f32 v[60:61], v[52:53], v[8:9], v[60:61] op_sel:[1,0,0] op_sel_hi:[1,1,1]
	v_pk_fma_f32 v[4:5], v[42:43], v[4:5], v[14:15] op_sel:[1,0,0] op_sel_hi:[1,1,1]
	v_pk_mul_f32 v[64:65], v[48:49], v[58:59] op_sel:[0,0] op_sel_hi:[0,1]
	v_add_f32_dpp v60, v61, v60 quad_perm:[1,0,3,2] row_mask:0xf bank_mask:0xf bound_ctrl:1
	v_pk_mul_f32 v[14:15], v[48:49], v[58:59] op_sel:[1,0] op_sel_hi:[1,1]
	v_pk_fma_f32 v[6:7], v[44:45], v[6:7], v[64:65] op_sel:[0,0,0] op_sel_hi:[0,1,1]
	v_add_f32_dpp v60, v60, v60 quad_perm:[2,3,0,1] row_mask:0xf bank_mask:0xf bound_ctrl:1
	v_add_f32_dpp v62, v63, v62 quad_perm:[1,0,3,2] row_mask:0xf bank_mask:0xf bound_ctrl:1
	v_pk_fma_f32 v[8:9], v[44:45], v[8:9], v[14:15] op_sel:[1,0,0] op_sel_hi:[1,1,1]
	v_add_f32_dpp v60, v60, v60 row_half_mirror row_mask:0xf bank_mask:0xf bound_ctrl:1
	v_add_f32_dpp v62, v62, v62 quad_perm:[2,3,0,1] row_mask:0xf bank_mask:0xf bound_ctrl:1
	ds_read_b128 v[32:35], v250 offset:16384
	v_add_f32_dpp v60, v60, v60 row_mirror row_mask:0xf bank_mask:0xf bound_ctrl:1
	v_add_f32_dpp v62, v62, v62 row_half_mirror row_mask:0xf bank_mask:0xf bound_ctrl:1
	ds_read_b128 v[16:19], v250 offset:15360
	v_mov_b32_dpp v61, v60 quad_perm:[1,0,3,2] row_mask:0xf bank_mask:0xf bound_ctrl:1
	v_add_f32_dpp v62, v62, v62 row_mirror row_mask:0xf bank_mask:0xf bound_ctrl:1
	s_waitcnt lgkmcnt(8)
; #define LAS __attribute__((address_space(3)))
; DI unsigned pk2(float a, float b) { f32x2 v = {a, b}; bf2_t r = __builtin_convertvector(v, bf2_t); return __builtin_bit_cast(unsigned, r); }
; DI f32x2 red16p(f32x2 x) { float a = x.x, b = x.y; red16x2(a, b); return (f32x2){a, b}; }
; DI void scan_bh2(const Args& a, int l, int bh, int halfsel, LAS unsigned char* lds) {
;     ...
;             for (int st = 0; st < T; ++st) {
;                 f32x4 nr4, nd4, nk4, nkk4, nb4; f32x2 nv2;
;                 if (st < T - 1) {
;                     const LAS float* o = cur + (st + 1) * 384;
;                     nr4 = *(const LAS f32x4*)(o + kq * 4); nd4 = *(const LAS f32x4*)(o + 64 + kq * 4); nk4 = *(const LAS f32x4*)(o + 128 + kq * 4);
;                     nkk4 = *(const LAS f32x4*)(o + 192 + kq * 4); nb4 = *(const LAS f32x4*)(o + 256 + kq * 4); nv2 = *(const LAS f32x2*)(o + 320 + row0);
;                 }
;                 f32x2 sa = S[0] * kk4[0]; sa += S[1] * kk4[1]; f32x2 sb = S[2] * kk4[2]; sb += S[3] * kk4[3]; sa += sb;
;                 sa = red16p(sa); sa = -sa;
; #pragma unroll
;                 for (int j = 0; j < 4; ++j) S[j] = S[j] * d4[j] + sa * b4[j] + v2 * k4[j];
;                 f32x2 y = S[0] * r4[0]; y += S[1] * r4[1]; f32x2 yc = S[2] * r4[2]; yc += S[3] * r4[3]; y += yc;
;                 y = red16p(y);
;                 *(LAS unsigned*)(yb + st * 128 + row0 * 2) = pk2(y.x, y.y);
	v_pk_fma_f32 v[2:3], v[54:55], v[60:61], v[2:3] op_sel:[0,0,0] op_sel_hi:[0,1,1] neg_lo:[0,1,0] neg_hi:[0,1,0]
	v_pk_fma_f32 v[4:5], v[54:55], v[60:61], v[4:5] op_sel:[1,0,0] op_sel_hi:[1,1,1] neg_lo:[0,1,0] neg_hi:[0,1,0]
	v_mov_b32_dpp v63, v62 quad_perm:[1,0,3,2] row_mask:0xf bank_mask:0xf bound_ctrl:1
	v_pk_fma_f32 v[6:7], v[56:57], v[60:61], v[6:7] op_sel:[0,0,0] op_sel_hi:[0,1,1] neg_lo:[0,1,0] neg_hi:[0,1,0]
	v_cvt_pk_bf16_f32 v64, v62, v63
	v_pk_fma_f32 v[8:9], v[56:57], v[60:61], v[8:9] op_sel:[1,0,0] op_sel_hi:[1,1,1] neg_lo:[0,1,0] neg_hi:[0,1,0]
	ds_write_b32 v253, v64 offset:1024
	v_pk_mul_f32 v[62:63], v[38:39], v[2:3] op_sel:[0,0] op_sel_hi:[0,1]
	ds_read_b128 v[50:53], v250 offset:17664
	v_pk_fma_f32 v[62:63], v[38:39], v[4:5], v[62:63] op_sel:[1,0,0] op_sel_hi:[1,1,1]
	ds_read_b32 v58, v251 offset:18176
	v_pk_fma_f32 v[62:63], v[40:41], v[6:7], v[62:63] op_sel:[0,0,0] op_sel_hi:[0,1,1]
	ds_read_b32 v59, v252 offset:18176
	v_pk_fma_f32 v[62:63], v[40:41], v[8:9], v[62:63] op_sel:[1,0,0] op_sel_hi:[1,1,1]
	ds_read_b128 v[46:49], v250 offset:17408
	ds_read_b128 v[42:45], v250 offset:17152
	s_waitcnt lgkmcnt(8)
	v_pk_mul_f32 v[60:61], v[28:29], v[2:3] op_sel:[0,0] op_sel_hi:[0,1]
	v_pk_mul_f32 v[64:65], v[24:25], v[36:37] op_sel:[0,0] op_sel_hi:[0,1]
	v_pk_fma_f32 v[60:61], v[28:29], v[4:5], v[60:61] op_sel:[1,0,0] op_sel_hi:[1,1,1]
	v_pk_mul_f32 v[14:15], v[24:25], v[36:37] op_sel:[1,0] op_sel_hi:[1,1]
	v_pk_fma_f32 v[60:61], v[30:31], v[6:7], v[60:61] op_sel:[0,0,0] op_sel_hi:[0,1,1]
	v_pk_fma_f32 v[2:3], v[20:21], v[2:3], v[64:65] op_sel:[0,0,0] op_sel_hi:[0,1,1]
	v_pk_fma_f32 v[60:61], v[30:31], v[8:9], v[60:61] op_sel:[1,0,0] op_sel_hi:[1,1,1]
	v_pk_fma_f32 v[4:5], v[20:21], v[4:5], v[14:15] op_sel:[1,0,0] op_sel_hi:[1,1,1]
	v_pk_mul_f32 v[64:65], v[26:27], v[36:37] op_sel:[0,0] op_sel_hi:[0,1]
	v_add_f32_dpp v60, v61, v60 quad_perm:[1,0,3,2] row_mask:0xf bank_mask:0xf bound_ctrl:1
	v_pk_mul_f32 v[14:15], v[26:27], v[36:37] op_sel:[1,0] op_sel_hi:[1,1]
	v_pk_fma_f32 v[6:7], v[22:23], v[6:7], v[64:65] op_sel:[0,0,0] op_sel_hi:[0,1,1]
	v_add_f32_dpp v60, v60, v60 quad_perm:[2,3,0,1] row_mask:0xf bank_mask:0xf bound_ctrl:1
	v_add_f32_dpp v62, v63, v62 quad_perm:[1,0,3,2] row_mask:0xf bank_mask:0xf bound_ctrl:1
	v_pk_fma_f32 v[8:9], v[22:23], v[8:9], v[14:15] op_sel:[1,0,0] op_sel_hi:[1,1,1]
	v_add_f32_dpp v60, v60, v60 row_half_mirror row_mask:0xf bank_mask:0xf bound_ctrl:1
	v_add_f32_dpp v62, v62, v62 quad_perm:[2,3,0,1] row_mask:0xf bank_mask:0xf bound_ctrl:1
	ds_read_b128 v[54:57], v250 offset:17920
	v_add_f32_dpp v60, v60, v60 row_mirror row_mask:0xf bank_mask:0xf bound_ctrl:1
	v_add_f32_dpp v62, v62, v62 row_half_mirror row_mask:0xf bank_mask:0xf bound_ctrl:1
	ds_read_b128 v[38:41], v250 offset:16896
	v_mov_b32_dpp v61, v60 quad_perm:[1,0,3,2] row_mask:0xf bank_mask:0xf bound_ctrl:1
	v_add_f32_dpp v62, v62, v62 row_mirror row_mask:0xf bank_mask:0xf bound_ctrl:1
	s_waitcnt lgkmcnt(8)
	v_pk_fma_f32 v[2:3], v[32:33], v[60:61], v[2:3] op_sel:[0,0,0] op_sel_hi:[0,1,1] neg_lo:[0,1,0] neg_hi:[0,1,0]
	v_pk_fma_f32 v[4:5], v[32:33], v[60:61], v[4:5] op_sel:[1,0,0] op_sel_hi:[1,1,1] neg_lo:[0,1,0] neg_hi:[0,1,0]
	v_mov_b32_dpp v63, v62 quad_perm:[1,0,3,2] row_mask:0xf bank_mask:0xf bound_ctrl:1
	v_pk_fma_f32 v[6:7], v[34:35], v[60:61], v[6:7] op_sel:[0,0,0] op_sel_hi:[0,1,1] neg_lo:[0,1,0] neg_hi:[0,1,0]
	v_cvt_pk_bf16_f32 v64, v62, v63
	v_pk_fma_f32 v[8:9], v[34:35], v[60:61], v[8:9] op_sel:[1,0,0] op_sel_hi:[1,1,1] neg_lo:[0,1,0] neg_hi:[0,1,0]
	ds_write_b32 v253, v64 offset:1152
	v_pk_mul_f32 v[62:63], v[16:17], v[2:3] op_sel:[0,0] op_sel_hi:[0,1]
	ds_read_b128 v[28:31], v250 offset:19200
	v_pk_fma_f32 v[62:63], v[16:17], v[4:5], v[62:63] op_sel:[1,0,0] op_sel_hi:[1,1,1]
	ds_read_b32 v36, v251 offset:19712
	v_pk_fma_f32 v[62:63], v[18:19], v[6:7], v[62:63] op_sel:[0,0,0] op_sel_hi:[0,1,1]
	ds_read_b32 v37, v252 offset:19712
	v_pk_fma_f32 v[62:63], v[18:19], v[8:9], v[62:63] op_sel:[1,0,0] op_sel_hi:[1,1,1]
	ds_read_b128 v[24:27], v250 offset:18944
	ds_read_b128 v[20:23], v250 offset:18688
	s_waitcnt lgkmcnt(8)
	v_pk_mul_f32 v[60:61], v[50:51], v[2:3] op_sel:[0,0] op_sel_hi:[0,1]
	v_pk_mul_f32 v[64:65], v[46:47], v[58:59] op_sel:[0,0] op_sel_hi:[0,1]
	v_pk_fma_f32 v[60:61], v[50:51], v[4:5], v[60:61] op_sel:[1,0,0] op_sel_hi:[1,1,1]
	v_pk_mul_f32 v[14:15], v[46:47], v[58:59] op_sel:[1,0] op_sel_hi:[1,1]
	v_pk_fma_f32 v[60:61], v[52:53], v[6:7], v[60:61] op_sel:[0,0,0] op_sel_hi:[0,1,1]
	v_pk_fma_f32 v[2:3], v[42:43], v[2:3], v[64:65] op_sel:[0,0,0] op_sel_hi:[0,1,1]
	v_pk_fma_f32 v[60:61], v[52:53], v[8:9], v[60:61] op_sel:[1,0,0] op_sel_hi:[1,1,1]
	v_pk_fma_f32 v[4:5], v[42:43], v[4:5], v[14:15] op_sel:[1,0,0] op_sel_hi:[1,1,1]
	v_pk_mul_f32 v[64:65], v[48:49], v[58:59] op_sel:[0,0] op_sel_hi:[0,1]
	v_add_f32_dpp v60, v61, v60 quad_perm:[1,0,3,2] row_mask:0xf bank_mask:0xf bound_ctrl:1
	v_pk_mul_f32 v[14:15], v[48:49], v[58:59] op_sel:[1,0] op_sel_hi:[1,1]
	v_pk_fma_f32 v[6:7], v[44:45], v[6:7], v[64:65] op_sel:[0,0,0] op_sel_hi:[0,1,1]
	v_add_f32_dpp v60, v60, v60 quad_perm:[2,3,0,1] row_mask:0xf bank_mask:0xf bound_ctrl:1
	v_add_f32_dpp v62, v63, v62 quad_perm:[1,0,3,2] row_mask:0xf bank_mask:0xf bound_ctrl:1
	v_pk_fma_f32 v[8:9], v[44:45], v[8:9], v[14:15] op_sel:[1,0,0] op_sel_hi:[1,1,1]
	v_add_f32_dpp v60, v60, v60 row_half_mirror row_mask:0xf bank_mask:0xf bound_ctrl:1
	v_add_f32_dpp v62, v62, v62 quad_perm:[2,3,0,1] row_mask:0xf bank_mask:0xf bound_ctrl:1
	ds_read_b128 v[32:35], v250 offset:19456
	v_add_f32_dpp v60, v60, v60 row_mirror row_mask:0xf bank_mask:0xf bound_ctrl:1
	v_add_f32_dpp v62, v62, v62 row_half_mirror row_mask:0xf bank_mask:0xf bound_ctrl:1
	ds_read_b128 v[16:19], v250 offset:18432
	v_mov_b32_dpp v61, v60 quad_perm:[1,0,3,2] row_mask:0xf bank_mask:0xf bound_ctrl:1
	v_add_f32_dpp v62, v62, v62 row_mirror row_mask:0xf bank_mask:0xf bound_ctrl:1
	s_waitcnt lgkmcnt(8)
; #define LAS __attribute__((address_space(3)))
; DI unsigned pk2(float a, float b) { f32x2 v = {a, b}; bf2_t r = __builtin_convertvector(v, bf2_t); return __builtin_bit_cast(unsigned, r); }
; DI f32x2 red16p(f32x2 x) { float a = x.x, b = x.y; red16x2(a, b); return (f32x2){a, b}; }
; DI void scan_bh2(const Args& a, int l, int bh, int halfsel, LAS unsigned char* lds) {
;     ...
;             for (int st = 0; st < T; ++st) {
;                 f32x4 nr4, nd4, nk4, nkk4, nb4; f32x2 nv2;
;                 if (st < T - 1) {
;                     const LAS float* o = cur + (st + 1) * 384;
;                     nr4 = *(const LAS f32x4*)(o + kq * 4); nd4 = *(const LAS f32x4*)(o + 64 + kq * 4); nk4 = *(const LAS f32x4*)(o + 128 + kq * 4);
;                     nkk4 = *(const LAS f32x4*)(o + 192 + kq * 4); nb4 = *(const LAS f32x4*)(o + 256 + kq * 4); nv2 = *(const LAS f32x2*)(o + 320 + row0);
;                 }
;                 f32x2 sa = S[0] * kk4[0]; sa += S[1] * kk4[1]; f32x2 sb = S[2] * kk4[2]; sb += S[3] * kk4[3]; sa += sb;
;                 sa = red16p(sa); sa = -sa;
; #pragma unroll
;                 for (int j = 0; j < 4; ++j) S[j] = S[j] * d4[j] + sa * b4[j] + v2 * k4[j];
;                 f32x2 y = S[0] * r4[0]; y += S[1] * r4[1]; f32x2 yc = S[2] * r4[2]; yc += S[3] * r4[3]; y += yc;
;                 y = red16p(y);
;                 *(LAS unsigned*)(yb + st * 128 + row0 * 2) = pk2(y.x, y.y);
	v_pk_fma_f32 v[2:3], v[54:55], v[60:61], v[2:3] op_sel:[0,0,0] op_sel_hi:[0,1,1] neg_lo:[0,1,0] neg_hi:[0,1,0]
	v_pk_fma_f32 v[4:5], v[54:55], v[60:61], v[4:5] op_sel:[1,0,0] op_sel_hi:[1,1,1] neg_lo:[0,1,0] neg_hi:[0,1,0]
	v_mov_b32_dpp v63, v62 quad_perm:[1,0,3,2] row_mask:0xf bank_mask:0xf bound_ctrl:1
	v_pk_fma_f32 v[6:7], v[56:57], v[60:61], v[6:7] op_sel:[0,0,0] op_sel_hi:[0,1,1] neg_lo:[0,1,0] neg_hi:[0,1,0]
	v_cvt_pk_bf16_f32 v64, v62, v63
	v_pk_fma_f32 v[8:9], v[56:57], v[60:61], v[8:9] op_sel:[1,0,0] op_sel_hi:[1,1,1] neg_lo:[0,1,0] neg_hi:[0,1,0]
	ds_write_b32 v253, v64 offset:1280
	v_pk_mul_f32 v[62:63], v[38:39], v[2:3] op_sel:[0,0] op_sel_hi:[0,1]
	ds_read_b128 v[50:53], v250 offset:20736
	v_pk_fma_f32 v[62:63], v[38:39], v[4:5], v[62:63] op_sel:[1,0,0] op_sel_hi:[1,1,1]
	ds_read_b32 v58, v251 offset:21248
	v_pk_fma_f32 v[62:63], v[40:41], v[6:7], v[62:63] op_sel:[0,0,0] op_sel_hi:[0,1,1]
	ds_read_b32 v59, v252 offset:21248
	v_pk_fma_f32 v[62:63], v[40:41], v[8:9], v[62:63] op_sel:[1,0,0] op_sel_hi:[1,1,1]
	ds_read_b128 v[46:49], v250 offset:20480
	ds_read_b128 v[42:45], v250 offset:20224
	s_waitcnt lgkmcnt(8)
	v_pk_mul_f32 v[60:61], v[28:29], v[2:3] op_sel:[0,0] op_sel_hi:[0,1]
	v_pk_mul_f32 v[64:65], v[24:25], v[36:37] op_sel:[0,0] op_sel_hi:[0,1]
	v_pk_fma_f32 v[60:61], v[28:29], v[4:5], v[60:61] op_sel:[1,0,0] op_sel_hi:[1,1,1]
	v_pk_mul_f32 v[14:15], v[24:25], v[36:37] op_sel:[1,0] op_sel_hi:[1,1]
	v_pk_fma_f32 v[60:61], v[30:31], v[6:7], v[60:61] op_sel:[0,0,0] op_sel_hi:[0,1,1]
	v_pk_fma_f32 v[2:3], v[20:21], v[2:3], v[64:65] op_sel:[0,0,0] op_sel_hi:[0,1,1]
	v_pk_fma_f32 v[60:61], v[30:31], v[8:9], v[60:61] op_sel:[1,0,0] op_sel_hi:[1,1,1]
	v_pk_fma_f32 v[4:5], v[20:21], v[4:5], v[14:15] op_sel:[1,0,0] op_sel_hi:[1,1,1]
	v_pk_mul_f32 v[64:65], v[26:27], v[36:37] op_sel:[0,0] op_sel_hi:[0,1]
	v_add_f32_dpp v60, v61, v60 quad_perm:[1,0,3,2] row_mask:0xf bank_mask:0xf bound_ctrl:1
	v_pk_mul_f32 v[14:15], v[26:27], v[36:37] op_sel:[1,0] op_sel_hi:[1,1]
	v_pk_fma_f32 v[6:7], v[22:23], v[6:7], v[64:65] op_sel:[0,0,0] op_sel_hi:[0,1,1]
	v_add_f32_dpp v60, v60, v60 quad_perm:[2,3,0,1] row_mask:0xf bank_mask:0xf bound_ctrl:1
	v_add_f32_dpp v62, v63, v62 quad_perm:[1,0,3,2] row_mask:0xf bank_mask:0xf bound_ctrl:1
	v_pk_fma_f32 v[8:9], v[22:23], v[8:9], v[14:15] op_sel:[1,0,0] op_sel_hi:[1,1,1]
	v_add_f32_dpp v60, v60, v60 row_half_mirror row_mask:0xf bank_mask:0xf bound_ctrl:1
	v_add_f32_dpp v62, v62, v62 quad_perm:[2,3,0,1] row_mask:0xf bank_mask:0xf bound_ctrl:1
	ds_read_b128 v[54:57], v250 offset:20992
	v_add_f32_dpp v60, v60, v60 row_mirror row_mask:0xf bank_mask:0xf bound_ctrl:1
	v_add_f32_dpp v62, v62, v62 row_half_mirror row_mask:0xf bank_mask:0xf bound_ctrl:1
	ds_read_b128 v[38:41], v250 offset:19968
	v_mov_b32_dpp v61, v60 quad_perm:[1,0,3,2] row_mask:0xf bank_mask:0xf bound_ctrl:1
	v_add_f32_dpp v62, v62, v62 row_mirror row_mask:0xf bank_mask:0xf bound_ctrl:1
	s_waitcnt lgkmcnt(8)
	v_pk_fma_f32 v[2:3], v[32:33], v[60:61], v[2:3] op_sel:[0,0,0] op_sel_hi:[0,1,1] neg_lo:[0,1,0] neg_hi:[0,1,0]
	v_pk_fma_f32 v[4:5], v[32:33], v[60:61], v[4:5] op_sel:[1,0,0] op_sel_hi:[1,1,1] neg_lo:[0,1,0] neg_hi:[0,1,0]
	v_mov_b32_dpp v63, v62 quad_perm:[1,0,3,2] row_mask:0xf bank_mask:0xf bound_ctrl:1
	v_pk_fma_f32 v[6:7], v[34:35], v[60:61], v[6:7] op_sel:[0,0,0] op_sel_hi:[0,1,1] neg_lo:[0,1,0] neg_hi:[0,1,0]
	v_cvt_pk_bf16_f32 v64, v62, v63
	v_pk_fma_f32 v[8:9], v[34:35], v[60:61], v[8:9] op_sel:[1,0,0] op_sel_hi:[1,1,1] neg_lo:[0,1,0] neg_hi:[0,1,0]
	ds_write_b32 v253, v64 offset:1408
	v_pk_mul_f32 v[62:63], v[16:17], v[2:3] op_sel:[0,0] op_sel_hi:[0,1]
	ds_read_b128 v[28:31], v250 offset:22272
	v_pk_fma_f32 v[62:63], v[16:17], v[4:5], v[62:63] op_sel:[1,0,0] op_sel_hi:[1,1,1]
	ds_read_b32 v36, v251 offset:22784
	v_pk_fma_f32 v[62:63], v[18:19], v[6:7], v[62:63] op_sel:[0,0,0] op_sel_hi:[0,1,1]
	ds_read_b32 v37, v252 offset:22784
	v_pk_fma_f32 v[62:63], v[18:19], v[8:9], v[62:63] op_sel:[1,0,0] op_sel_hi:[1,1,1]
	ds_read_b128 v[24:27], v250 offset:22016
	ds_read_b128 v[20:23], v250 offset:21760
	s_waitcnt lgkmcnt(8)
	v_pk_mul_f32 v[60:61], v[50:51], v[2:3] op_sel:[0,0] op_sel_hi:[0,1]
	v_pk_mul_f32 v[64:65], v[46:47], v[58:59] op_sel:[0,0] op_sel_hi:[0,1]
	v_pk_fma_f32 v[60:61], v[50:51], v[4:5], v[60:61] op_sel:[1,0,0] op_sel_hi:[1,1,1]
	v_pk_mul_f32 v[14:15], v[46:47], v[58:59] op_sel:[1,0] op_sel_hi:[1,1]
	v_pk_fma_f32 v[60:61], v[52:53], v[6:7], v[60:61] op_sel:[0,0,0] op_sel_hi:[0,1,1]
	v_pk_fma_f32 v[2:3], v[42:43], v[2:3], v[64:65] op_sel:[0,0,0] op_sel_hi:[0,1,1]
	v_pk_fma_f32 v[60:61], v[52:53], v[8:9], v[60:61] op_sel:[1,0,0] op_sel_hi:[1,1,1]
	v_pk_fma_f32 v[4:5], v[42:43], v[4:5], v[14:15] op_sel:[1,0,0] op_sel_hi:[1,1,1]
	v_pk_mul_f32 v[64:65], v[48:49], v[58:59] op_sel:[0,0] op_sel_hi:[0,1]
	v_add_f32_dpp v60, v61, v60 quad_perm:[1,0,3,2] row_mask:0xf bank_mask:0xf bound_ctrl:1
	v_pk_mul_f32 v[14:15], v[48:49], v[58:59] op_sel:[1,0] op_sel_hi:[1,1]
	v_pk_fma_f32 v[6:7], v[44:45], v[6:7], v[64:65] op_sel:[0,0,0] op_sel_hi:[0,1,1]
	v_add_f32_dpp v60, v60, v60 quad_perm:[2,3,0,1] row_mask:0xf bank_mask:0xf bound_ctrl:1
	v_add_f32_dpp v62, v63, v62 quad_perm:[1,0,3,2] row_mask:0xf bank_mask:0xf bound_ctrl:1
	v_pk_fma_f32 v[8:9], v[44:45], v[8:9], v[14:15] op_sel:[1,0,0] op_sel_hi:[1,1,1]
	v_add_f32_dpp v60, v60, v60 row_half_mirror row_mask:0xf bank_mask:0xf bound_ctrl:1
	v_add_f32_dpp v62, v62, v62 quad_perm:[2,3,0,1] row_mask:0xf bank_mask:0xf bound_ctrl:1
	ds_read_b128 v[32:35], v250 offset:22528
	v_add_f32_dpp v60, v60, v60 row_mirror row_mask:0xf bank_mask:0xf bound_ctrl:1
	v_add_f32_dpp v62, v62, v62 row_half_mirror row_mask:0xf bank_mask:0xf bound_ctrl:1
	ds_read_b128 v[16:19], v250 offset:21504
	v_mov_b32_dpp v61, v60 quad_perm:[1,0,3,2] row_mask:0xf bank_mask:0xf bound_ctrl:1
	v_add_f32_dpp v62, v62, v62 row_mirror row_mask:0xf bank_mask:0xf bound_ctrl:1
	s_waitcnt lgkmcnt(8)
; #define LAS __attribute__((address_space(3)))
; DI unsigned pk2(float a, float b) { f32x2 v = {a, b}; bf2_t r = __builtin_convertvector(v, bf2_t); return __builtin_bit_cast(unsigned, r); }
; DI f32x2 red16p(f32x2 x) { float a = x.x, b = x.y; red16x2(a, b); return (f32x2){a, b}; }
; DI void scan_bh2(const Args& a, int l, int bh, int halfsel, LAS unsigned char* lds) {
;     ...
;             for (int st = 0; st < T; ++st) {
;                 f32x4 nr4, nd4, nk4, nkk4, nb4; f32x2 nv2;
;                 if (st < T - 1) {
;                     const LAS float* o = cur + (st + 1) * 384;
;                     nr4 = *(const LAS f32x4*)(o + kq * 4); nd4 = *(const LAS f32x4*)(o + 64 + kq * 4); nk4 = *(const LAS f32x4*)(o + 128 + kq * 4);
;                     nkk4 = *(const LAS f32x4*)(o + 192 + kq * 4); nb4 = *(const LAS f32x4*)(o + 256 + kq * 4); nv2 = *(const LAS f32x2*)(o + 320 + row0);
;                 }
;                 f32x2 sa = S[0] * kk4[0]; sa += S[1] * kk4[1]; f32x2 sb = S[2] * kk4[2]; sb += S[3] * kk4[3]; sa += sb;
;                 sa = red16p(sa); sa = -sa;
; #pragma unroll
;                 for (int j = 0; j < 4; ++j) S[j] = S[j] * d4[j] + sa * b4[j] + v2 * k4[j];
;                 f32x2 y = S[0] * r4[0]; y += S[1] * r4[1]; f32x2 yc = S[2] * r4[2]; yc += S[3] * r4[3]; y += yc;
;                 y = red16p(y);
;                 *(LAS unsigned*)(yb + st * 128 + row0 * 2) = pk2(y.x, y.y);
;                 if (st < T - 1) { r4 = nr4; d4 = nd4; k4 = nk4; kk4 = nkk4; b4 = nb4; v2 = nv2; }
	v_pk_fma_f32 v[2:3], v[54:55], v[60:61], v[2:3] op_sel:[0,0,0] op_sel_hi:[0,1,1] neg_lo:[0,1,0] neg_hi:[0,1,0]
	v_pk_fma_f32 v[4:5], v[54:55], v[60:61], v[4:5] op_sel:[1,0,0] op_sel_hi:[1,1,1] neg_lo:[0,1,0] neg_hi:[0,1,0]
	v_mov_b32_dpp v63, v62 quad_perm:[1,0,3,2] row_mask:0xf bank_mask:0xf bound_ctrl:1
	v_pk_fma_f32 v[6:7], v[56:57], v[60:61], v[6:7] op_sel:[0,0,0] op_sel_hi:[0,1,1] neg_lo:[0,1,0] neg_hi:[0,1,0]
	v_cvt_pk_bf16_f32 v64, v62, v63
	v_pk_fma_f32 v[8:9], v[56:57], v[60:61], v[8:9] op_sel:[1,0,0] op_sel_hi:[1,1,1] neg_lo:[0,1,0] neg_hi:[0,1,0]
	ds_write_b32 v253, v64 offset:1536
	v_pk_mul_f32 v[62:63], v[38:39], v[2:3] op_sel:[0,0] op_sel_hi:[0,1]
	ds_read_b128 v[50:53], v250 offset:23808
	v_pk_fma_f32 v[62:63], v[38:39], v[4:5], v[62:63] op_sel:[1,0,0] op_sel_hi:[1,1,1]
	ds_read_b32 v58, v251 offset:24320
	v_pk_fma_f32 v[62:63], v[40:41], v[6:7], v[62:63] op_sel:[0,0,0] op_sel_hi:[0,1,1]
	ds_read_b32 v59, v252 offset:24320
	v_pk_fma_f32 v[62:63], v[40:41], v[8:9], v[62:63] op_sel:[1,0,0] op_sel_hi:[1,1,1]
	ds_read_b128 v[46:49], v250 offset:23552
	ds_read_b128 v[42:45], v250 offset:23296
	s_waitcnt lgkmcnt(8)
	v_pk_mul_f32 v[60:61], v[28:29], v[2:3] op_sel:[0,0] op_sel_hi:[0,1]
	v_pk_mul_f32 v[64:65], v[24:25], v[36:37] op_sel:[0,0] op_sel_hi:[0,1]
	v_pk_fma_f32 v[60:61], v[28:29], v[4:5], v[60:61] op_sel:[1,0,0] op_sel_hi:[1,1,1]
	v_pk_mul_f32 v[14:15], v[24:25], v[36:37] op_sel:[1,0] op_sel_hi:[1,1]
	v_pk_fma_f32 v[60:61], v[30:31], v[6:7], v[60:61] op_sel:[0,0,0] op_sel_hi:[0,1,1]
	v_pk_fma_f32 v[2:3], v[20:21], v[2:3], v[64:65] op_sel:[0,0,0] op_sel_hi:[0,1,1]
	v_pk_fma_f32 v[60:61], v[30:31], v[8:9], v[60:61] op_sel:[1,0,0] op_sel_hi:[1,1,1]
	v_pk_fma_f32 v[4:5], v[20:21], v[4:5], v[14:15] op_sel:[1,0,0] op_sel_hi:[1,1,1]
	v_pk_mul_f32 v[64:65], v[26:27], v[36:37] op_sel:[0,0] op_sel_hi:[0,1]
	v_add_f32_dpp v60, v61, v60 quad_perm:[1,0,3,2] row_mask:0xf bank_mask:0xf bound_ctrl:1
	v_pk_mul_f32 v[14:15], v[26:27], v[36:37] op_sel:[1,0] op_sel_hi:[1,1]
	v_pk_fma_f32 v[6:7], v[22:23], v[6:7], v[64:65] op_sel:[0,0,0] op_sel_hi:[0,1,1]
	v_add_f32_dpp v60, v60, v60 quad_perm:[2,3,0,1] row_mask:0xf bank_mask:0xf bound_ctrl:1
	v_add_f32_dpp v62, v63, v62 quad_perm:[1,0,3,2] row_mask:0xf bank_mask:0xf bound_ctrl:1
	v_pk_fma_f32 v[8:9], v[22:23], v[8:9], v[14:15] op_sel:[1,0,0] op_sel_hi:[1,1,1]
	v_add_f32_dpp v60, v60, v60 row_half_mirror row_mask:0xf bank_mask:0xf bound_ctrl:1
	v_add_f32_dpp v62, v62, v62 quad_perm:[2,3,0,1] row_mask:0xf bank_mask:0xf bound_ctrl:1
	ds_read_b128 v[54:57], v250 offset:24064
	v_add_f32_dpp v60, v60, v60 row_mirror row_mask:0xf bank_mask:0xf bound_ctrl:1
	v_add_f32_dpp v62, v62, v62 row_half_mirror row_mask:0xf bank_mask:0xf bound_ctrl:1
	ds_read_b128 v[38:41], v250 offset:23040
	v_mov_b32_dpp v61, v60 quad_perm:[1,0,3,2] row_mask:0xf bank_mask:0xf bound_ctrl:1
	v_add_f32_dpp v62, v62, v62 row_mirror row_mask:0xf bank_mask:0xf bound_ctrl:1
	s_waitcnt lgkmcnt(8)
	v_pk_fma_f32 v[2:3], v[32:33], v[60:61], v[2:3] op_sel:[0,0,0] op_sel_hi:[0,1,1] neg_lo:[0,1,0] neg_hi:[0,1,0]
	v_pk_fma_f32 v[4:5], v[32:33], v[60:61], v[4:5] op_sel:[1,0,0] op_sel_hi:[1,1,1] neg_lo:[0,1,0] neg_hi:[0,1,0]
	v_mov_b32_dpp v63, v62 quad_perm:[1,0,3,2] row_mask:0xf bank_mask:0xf bound_ctrl:1
	v_pk_fma_f32 v[6:7], v[34:35], v[60:61], v[6:7] op_sel:[0,0,0] op_sel_hi:[0,1,1] neg_lo:[0,1,0] neg_hi:[0,1,0]
	v_cvt_pk_bf16_f32 v64, v62, v63
	v_pk_fma_f32 v[8:9], v[34:35], v[60:61], v[8:9] op_sel:[1,0,0] op_sel_hi:[1,1,1] neg_lo:[0,1,0] neg_hi:[0,1,0]
	ds_write_b32 v253, v64 offset:1664
	v_pk_mul_f32 v[62:63], v[16:17], v[2:3] op_sel:[0,0] op_sel_hi:[0,1]
	ds_read_b128 v[28:31], v250 offset:25344
	v_pk_fma_f32 v[62:63], v[16:17], v[4:5], v[62:63] op_sel:[1,0,0] op_sel_hi:[1,1,1]
	ds_read_b32 v36, v251 offset:25856
	v_pk_fma_f32 v[62:63], v[18:19], v[6:7], v[62:63] op_sel:[0,0,0] op_sel_hi:[0,1,1]
	ds_read_b32 v37, v252 offset:25856
	v_pk_fma_f32 v[62:63], v[18:19], v[8:9], v[62:63] op_sel:[1,0,0] op_sel_hi:[1,1,1]
	ds_read_b128 v[24:27], v250 offset:25088
	ds_read_b128 v[20:23], v250 offset:24832
	s_waitcnt lgkmcnt(8)
	v_pk_mul_f32 v[60:61], v[50:51], v[2:3] op_sel:[0,0] op_sel_hi:[0,1]
	v_pk_mul_f32 v[64:65], v[46:47], v[58:59] op_sel:[0,0] op_sel_hi:[0,1]
	v_pk_fma_f32 v[60:61], v[50:51], v[4:5], v[60:61] op_sel:[1,0,0] op_sel_hi:[1,1,1]
	v_pk_mul_f32 v[14:15], v[46:47], v[58:59] op_sel:[1,0] op_sel_hi:[1,1]
	v_pk_fma_f32 v[60:61], v[52:53], v[6:7], v[60:61] op_sel:[0,0,0] op_sel_hi:[0,1,1]
	v_pk_fma_f32 v[2:3], v[42:43], v[2:3], v[64:65] op_sel:[0,0,0] op_sel_hi:[0,1,1]
	v_pk_fma_f32 v[60:61], v[52:53], v[8:9], v[60:61] op_sel:[1,0,0] op_sel_hi:[1,1,1]
	v_pk_fma_f32 v[4:5], v[42:43], v[4:5], v[14:15] op_sel:[1,0,0] op_sel_hi:[1,1,1]
	v_pk_mul_f32 v[64:65], v[48:49], v[58:59] op_sel:[0,0] op_sel_hi:[0,1]
	v_add_f32_dpp v60, v61, v60 quad_perm:[1,0,3,2] row_mask:0xf bank_mask:0xf bound_ctrl:1
	v_pk_mul_f32 v[14:15], v[48:49], v[58:59] op_sel:[1,0] op_sel_hi:[1,1]
	v_pk_fma_f32 v[6:7], v[44:45], v[6:7], v[64:65] op_sel:[0,0,0] op_sel_hi:[0,1,1]
	v_add_f32_dpp v60, v60, v60 quad_perm:[2,3,0,1] row_mask:0xf bank_mask:0xf bound_ctrl:1
	v_add_f32_dpp v62, v63, v62 quad_perm:[1,0,3,2] row_mask:0xf bank_mask:0xf bound_ctrl:1
	v_pk_fma_f32 v[8:9], v[44:45], v[8:9], v[14:15] op_sel:[1,0,0] op_sel_hi:[1,1,1]
	v_add_f32_dpp v60, v60, v60 row_half_mirror row_mask:0xf bank_mask:0xf bound_ctrl:1
	v_add_f32_dpp v62, v62, v62 quad_perm:[2,3,0,1] row_mask:0xf bank_mask:0xf bound_ctrl:1
	ds_read_b128 v[32:35], v250 offset:25600
	v_add_f32_dpp v60, v60, v60 row_mirror row_mask:0xf bank_mask:0xf bound_ctrl:1
	v_add_f32_dpp v62, v62, v62 row_half_mirror row_mask:0xf bank_mask:0xf bound_ctrl:1
	ds_read_b128 v[16:19], v250 offset:24576
	v_mov_b32_dpp v61, v60 quad_perm:[1,0,3,2] row_mask:0xf bank_mask:0xf bound_ctrl:1
	v_add_f32_dpp v62, v62, v62 row_mirror row_mask:0xf bank_mask:0xf bound_ctrl:1
	s_waitcnt lgkmcnt(8)
; #define LAS __attribute__((address_space(3)))
; DI unsigned pk2(float a, float b) { f32x2 v = {a, b}; bf2_t r = __builtin_convertvector(v, bf2_t); return __builtin_bit_cast(unsigned, r); }
; DI f32x2 red16p(f32x2 x) { float a = x.x, b = x.y; red16x2(a, b); return (f32x2){a, b}; }
; DI void scan_bh2(const Args& a, int l, int bh, int halfsel, LAS unsigned char* lds) {
;     ...
;             for (int st = 0; st < T; ++st) {
;                 f32x4 nr4, nd4, nk4, nkk4, nb4; f32x2 nv2;
;                 if (st < T - 1) {
;                     const LAS float* o = cur + (st + 1) * 384;
;                     nr4 = *(const LAS f32x4*)(o + kq * 4); nd4 = *(const LAS f32x4*)(o + 64 + kq * 4); nk4 = *(const LAS f32x4*)(o + 128 + kq * 4);
;                     nkk4 = *(const LAS f32x4*)(o + 192 + kq * 4); nb4 = *(const LAS f32x4*)(o + 256 + kq * 4); nv2 = *(const LAS f32x2*)(o + 320 + row0);
;                 }
;                 f32x2 sa = S[0] * kk4[0]; sa += S[1] * kk4[1]; f32x2 sb = S[2] * kk4[2]; sb += S[3] * kk4[3]; sa += sb;
;                 sa = red16p(sa); sa = -sa;
; #pragma unroll
;                 for (int j = 0; j < 4; ++j) S[j] = S[j] * d4[j] + sa * b4[j] + v2 * k4[j];
;                 f32x2 y = S[0] * r4[0]; y += S[1] * r4[1]; f32x2 yc = S[2] * r4[2]; yc += S[3] * r4[3]; y += yc;
;                 y = red16p(y);
;                 *(LAS unsigned*)(yb + st * 128 + row0 * 2) = pk2(y.x, y.y);
;                 if (st < T - 1) { r4 = nr4; d4 = nd4; k4 = nk4; kk4 = nkk4; b4 = nb4; v2 = nv2; }
	v_pk_fma_f32 v[2:3], v[54:55], v[60:61], v[2:3] op_sel:[0,0,0] op_sel_hi:[0,1,1] neg_lo:[0,1,0] neg_hi:[0,1,0]
	v_pk_fma_f32 v[4:5], v[54:55], v[60:61], v[4:5] op_sel:[1,0,0] op_sel_hi:[1,1,1] neg_lo:[0,1,0] neg_hi:[0,1,0]
	v_mov_b32_dpp v63, v62 quad_perm:[1,0,3,2] row_mask:0xf bank_mask:0xf bound_ctrl:1
	v_pk_fma_f32 v[6:7], v[56:57], v[60:61], v[6:7] op_sel:[0,0,0] op_sel_hi:[0,1,1] neg_lo:[0,1,0] neg_hi:[0,1,0]
	v_cvt_pk_bf16_f32 v64, v62, v63
	v_pk_fma_f32 v[8:9], v[56:57], v[60:61], v[8:9] op_sel:[1,0,0] op_sel_hi:[1,1,1] neg_lo:[0,1,0] neg_hi:[0,1,0]
	ds_write_b32 v253, v64 offset:1792
	v_pk_mul_f32 v[62:63], v[38:39], v[2:3] op_sel:[0,0] op_sel_hi:[0,1]
	ds_read_b128 v[50:53], v250 offset:26880
	v_pk_fma_f32 v[62:63], v[38:39], v[4:5], v[62:63] op_sel:[1,0,0] op_sel_hi:[1,1,1]
	ds_read_b32 v58, v251 offset:27392
	v_pk_fma_f32 v[62:63], v[40:41], v[6:7], v[62:63] op_sel:[0,0,0] op_sel_hi:[0,1,1]
	ds_read_b32 v59, v252 offset:27392
	v_pk_fma_f32 v[62:63], v[40:41], v[8:9], v[62:63] op_sel:[1,0,0] op_sel_hi:[1,1,1]
	ds_read_b128 v[46:49], v250 offset:26624
	ds_read_b128 v[42:45], v250 offset:26368
	s_waitcnt lgkmcnt(8)
	v_pk_mul_f32 v[60:61], v[28:29], v[2:3] op_sel:[0,0] op_sel_hi:[0,1]
	v_pk_mul_f32 v[64:65], v[24:25], v[36:37] op_sel:[0,0] op_sel_hi:[0,1]
	v_pk_fma_f32 v[60:61], v[28:29], v[4:5], v[60:61] op_sel:[1,0,0] op_sel_hi:[1,1,1]
	v_pk_mul_f32 v[14:15], v[24:25], v[36:37] op_sel:[1,0] op_sel_hi:[1,1]
	v_pk_fma_f32 v[60:61], v[30:31], v[6:7], v[60:61] op_sel:[0,0,0] op_sel_hi:[0,1,1]
	v_pk_fma_f32 v[2:3], v[20:21], v[2:3], v[64:65] op_sel:[0,0,0] op_sel_hi:[0,1,1]
	v_pk_fma_f32 v[60:61], v[30:31], v[8:9], v[60:61] op_sel:[1,0,0] op_sel_hi:[1,1,1]
	v_pk_fma_f32 v[4:5], v[20:21], v[4:5], v[14:15] op_sel:[1,0,0] op_sel_hi:[1,1,1]
	v_pk_mul_f32 v[64:65], v[26:27], v[36:37] op_sel:[0,0] op_sel_hi:[0,1]
	v_add_f32_dpp v60, v61, v60 quad_perm:[1,0,3,2] row_mask:0xf bank_mask:0xf bound_ctrl:1
	v_pk_mul_f32 v[14:15], v[26:27], v[36:37] op_sel:[1,0] op_sel_hi:[1,1]
	v_pk_fma_f32 v[6:7], v[22:23], v[6:7], v[64:65] op_sel:[0,0,0] op_sel_hi:[0,1,1]
	v_add_f32_dpp v60, v60, v60 quad_perm:[2,3,0,1] row_mask:0xf bank_mask:0xf bound_ctrl:1
	v_add_f32_dpp v62, v63, v62 quad_perm:[1,0,3,2] row_mask:0xf bank_mask:0xf bound_ctrl:1
	v_pk_fma_f32 v[8:9], v[22:23], v[8:9], v[14:15] op_sel:[1,0,0] op_sel_hi:[1,1,1]
	v_add_f32_dpp v60, v60, v60 row_half_mirror row_mask:0xf bank_mask:0xf bound_ctrl:1
	v_add_f32_dpp v62, v62, v62 quad_perm:[2,3,0,1] row_mask:0xf bank_mask:0xf bound_ctrl:1
	ds_read_b128 v[54:57], v250 offset:27136
	v_add_f32_dpp v60, v60, v60 row_mirror row_mask:0xf bank_mask:0xf bound_ctrl:1
	v_add_f32_dpp v62, v62, v62 row_half_mirror row_mask:0xf bank_mask:0xf bound_ctrl:1
	ds_read_b128 v[38:41], v250 offset:26112
	v_mov_b32_dpp v61, v60 quad_perm:[1,0,3,2] row_mask:0xf bank_mask:0xf bound_ctrl:1
	v_add_f32_dpp v62, v62, v62 row_mirror row_mask:0xf bank_mask:0xf bound_ctrl:1
	s_waitcnt lgkmcnt(8)
	v_pk_fma_f32 v[2:3], v[32:33], v[60:61], v[2:3] op_sel:[0,0,0] op_sel_hi:[0,1,1] neg_lo:[0,1,0] neg_hi:[0,1,0]
	v_pk_fma_f32 v[4:5], v[32:33], v[60:61], v[4:5] op_sel:[1,0,0] op_sel_hi:[1,1,1] neg_lo:[0,1,0] neg_hi:[0,1,0]
	v_mov_b32_dpp v63, v62 quad_perm:[1,0,3,2] row_mask:0xf bank_mask:0xf bound_ctrl:1
	v_pk_fma_f32 v[6:7], v[34:35], v[60:61], v[6:7] op_sel:[0,0,0] op_sel_hi:[0,1,1] neg_lo:[0,1,0] neg_hi:[0,1,0]
	v_cvt_pk_bf16_f32 v64, v62, v63
	v_pk_fma_f32 v[8:9], v[34:35], v[60:61], v[8:9] op_sel:[1,0,0] op_sel_hi:[1,1,1] neg_lo:[0,1,0] neg_hi:[0,1,0]
	ds_write_b32 v253, v64 offset:1920
	v_pk_mul_f32 v[62:63], v[16:17], v[2:3] op_sel:[0,0] op_sel_hi:[0,1]
	ds_read_b128 v[28:31], v250 offset:28416
	v_pk_fma_f32 v[62:63], v[16:17], v[4:5], v[62:63] op_sel:[1,0,0] op_sel_hi:[1,1,1]
	ds_read_b32 v36, v251 offset:28928
	v_pk_fma_f32 v[62:63], v[18:19], v[6:7], v[62:63] op_sel:[0,0,0] op_sel_hi:[0,1,1]
	ds_read_b32 v37, v252 offset:28928
	v_pk_fma_f32 v[62:63], v[18:19], v[8:9], v[62:63] op_sel:[1,0,0] op_sel_hi:[1,1,1]
	ds_read_b128 v[24:27], v250 offset:28160
	ds_read_b128 v[20:23], v250 offset:27904
	s_waitcnt lgkmcnt(8)
	v_pk_mul_f32 v[60:61], v[50:51], v[2:3] op_sel:[0,0] op_sel_hi:[0,1]
	v_pk_mul_f32 v[64:65], v[46:47], v[58:59] op_sel:[0,0] op_sel_hi:[0,1]
	v_pk_fma_f32 v[60:61], v[50:51], v[4:5], v[60:61] op_sel:[1,0,0] op_sel_hi:[1,1,1]
	v_pk_mul_f32 v[14:15], v[46:47], v[58:59] op_sel:[1,0] op_sel_hi:[1,1]
	v_pk_fma_f32 v[60:61], v[52:53], v[6:7], v[60:61] op_sel:[0,0,0] op_sel_hi:[0,1,1]
	v_pk_fma_f32 v[2:3], v[42:43], v[2:3], v[64:65] op_sel:[0,0,0] op_sel_hi:[0,1,1]
	v_pk_fma_f32 v[60:61], v[52:53], v[8:9], v[60:61] op_sel:[1,0,0] op_sel_hi:[1,1,1]
	v_pk_fma_f32 v[4:5], v[42:43], v[4:5], v[14:15] op_sel:[1,0,0] op_sel_hi:[1,1,1]
	v_pk_mul_f32 v[64:65], v[48:49], v[58:59] op_sel:[0,0] op_sel_hi:[0,1]
	v_add_f32_dpp v60, v61, v60 quad_perm:[1,0,3,2] row_mask:0xf bank_mask:0xf bound_ctrl:1
	v_pk_mul_f32 v[14:15], v[48:49], v[58:59] op_sel:[1,0] op_sel_hi:[1,1]
	v_pk_fma_f32 v[6:7], v[44:45], v[6:7], v[64:65] op_sel:[0,0,0] op_sel_hi:[0,1,1]
	v_add_f32_dpp v60, v60, v60 quad_perm:[2,3,0,1] row_mask:0xf bank_mask:0xf bound_ctrl:1
	v_add_f32_dpp v62, v63, v62 quad_perm:[1,0,3,2] row_mask:0xf bank_mask:0xf bound_ctrl:1
	v_pk_fma_f32 v[8:9], v[44:45], v[8:9], v[14:15] op_sel:[1,0,0] op_sel_hi:[1,1,1]
	v_add_f32_dpp v60, v60, v60 row_half_mirror row_mask:0xf bank_mask:0xf bound_ctrl:1
	v_add_f32_dpp v62, v62, v62 quad_perm:[2,3,0,1] row_mask:0xf bank_mask:0xf bound_ctrl:1
	ds_read_b128 v[32:35], v250 offset:28672
	v_add_f32_dpp v60, v60, v60 row_mirror row_mask:0xf bank_mask:0xf bound_ctrl:1
	v_add_f32_dpp v62, v62, v62 row_half_mirror row_mask:0xf bank_mask:0xf bound_ctrl:1
	ds_read_b128 v[16:19], v250 offset:27648
	v_mov_b32_dpp v61, v60 quad_perm:[1,0,3,2] row_mask:0xf bank_mask:0xf bound_ctrl:1
	v_add_f32_dpp v62, v62, v62 row_mirror row_mask:0xf bank_mask:0xf bound_ctrl:1
	s_waitcnt lgkmcnt(8)
; #define LAS __attribute__((address_space(3)))
; DI unsigned pk2(float a, float b) { f32x2 v = {a, b}; bf2_t r = __builtin_convertvector(v, bf2_t); return __builtin_bit_cast(unsigned, r); }
; DI f32x2 red16p(f32x2 x) { float a = x.x, b = x.y; red16x2(a, b); return (f32x2){a, b}; }
; DI void scan_bh2(const Args& a, int l, int bh, int halfsel, LAS unsigned char* lds) {
;     ...
;             for (int st = 0; st < T; ++st) {
;                 f32x4 nr4, nd4, nk4, nkk4, nb4; f32x2 nv2;
;                 if (st < T - 1) {
;                     const LAS float* o = cur + (st + 1) * 384;
;                     nr4 = *(const LAS f32x4*)(o + kq * 4); nd4 = *(const LAS f32x4*)(o + 64 + kq * 4); nk4 = *(const LAS f32x4*)(o + 128 + kq * 4);
;                     nkk4 = *(const LAS f32x4*)(o + 192 + kq * 4); nb4 = *(const LAS f32x4*)(o + 256 + kq * 4); nv2 = *(const LAS f32x2*)(o + 320 + row0);
;                 }
;                 f32x2 sa = S[0] * kk4[0]; sa += S[1] * kk4[1]; f32x2 sb = S[2] * kk4[2]; sb += S[3] * kk4[3]; sa += sb;
;                 sa = red16p(sa); sa = -sa;
; #pragma unroll
;                 for (int j = 0; j < 4; ++j) S[j] = S[j] * d4[j] + sa * b4[j] + v2 * k4[j];
;                 f32x2 y = S[0] * r4[0]; y += S[1] * r4[1]; f32x2 yc = S[2] * r4[2]; yc += S[3] * r4[3]; y += yc;
;                 y = red16p(y);
;                 *(LAS unsigned*)(yb + st * 128 + row0 * 2) = pk2(y.x, y.y);
;                 if (st < T - 1) { r4 = nr4; d4 = nd4; k4 = nk4; kk4 = nkk4; b4 = nb4; v2 = nv2; }
	v_pk_fma_f32 v[2:3], v[54:55], v[60:61], v[2:3] op_sel:[0,0,0] op_sel_hi:[0,1,1] neg_lo:[0,1,0] neg_hi:[0,1,0]
	v_pk_fma_f32 v[4:5], v[54:55], v[60:61], v[4:5] op_sel:[1,0,0] op_sel_hi:[1,1,1] neg_lo:[0,1,0] neg_hi:[0,1,0]
	v_mov_b32_dpp v63, v62 quad_perm:[1,0,3,2] row_mask:0xf bank_mask:0xf bound_ctrl:1
	v_pk_fma_f32 v[6:7], v[56:57], v[60:61], v[6:7] op_sel:[0,0,0] op_sel_hi:[0,1,1] neg_lo:[0,1,0] neg_hi:[0,1,0]
	v_cvt_pk_bf16_f32 v64, v62, v63
	v_pk_fma_f32 v[8:9], v[56:57], v[60:61], v[8:9] op_sel:[1,0,0] op_sel_hi:[1,1,1] neg_lo:[0,1,0] neg_hi:[0,1,0]
	ds_write_b32 v253, v64 offset:2048
	v_pk_mul_f32 v[62:63], v[38:39], v[2:3] op_sel:[0,0] op_sel_hi:[0,1]
	ds_read_b128 v[50:53], v250 offset:29952
	v_pk_fma_f32 v[62:63], v[38:39], v[4:5], v[62:63] op_sel:[1,0,0] op_sel_hi:[1,1,1]
	ds_read_b32 v58, v251 offset:30464
	v_pk_fma_f32 v[62:63], v[40:41], v[6:7], v[62:63] op_sel:[0,0,0] op_sel_hi:[0,1,1]
	ds_read_b32 v59, v252 offset:30464
	v_pk_fma_f32 v[62:63], v[40:41], v[8:9], v[62:63] op_sel:[1,0,0] op_sel_hi:[1,1,1]
	ds_read_b128 v[46:49], v250 offset:29696
	ds_read_b128 v[42:45], v250 offset:29440
	s_waitcnt lgkmcnt(8)
	v_pk_mul_f32 v[60:61], v[28:29], v[2:3] op_sel:[0,0] op_sel_hi:[0,1]
	v_pk_mul_f32 v[64:65], v[24:25], v[36:37] op_sel:[0,0] op_sel_hi:[0,1]
	v_pk_fma_f32 v[60:61], v[28:29], v[4:5], v[60:61] op_sel:[1,0,0] op_sel_hi:[1,1,1]
	v_pk_mul_f32 v[14:15], v[24:25], v[36:37] op_sel:[1,0] op_sel_hi:[1,1]
	v_pk_fma_f32 v[60:61], v[30:31], v[6:7], v[60:61] op_sel:[0,0,0] op_sel_hi:[0,1,1]
	v_pk_fma_f32 v[2:3], v[20:21], v[2:3], v[64:65] op_sel:[0,0,0] op_sel_hi:[0,1,1]
	v_pk_fma_f32 v[60:61], v[30:31], v[8:9], v[60:61] op_sel:[1,0,0] op_sel_hi:[1,1,1]
	v_pk_fma_f32 v[4:5], v[20:21], v[4:5], v[14:15] op_sel:[1,0,0] op_sel_hi:[1,1,1]
	v_pk_mul_f32 v[64:65], v[26:27], v[36:37] op_sel:[0,0] op_sel_hi:[0,1]
	v_add_f32_dpp v60, v61, v60 quad_perm:[1,0,3,2] row_mask:0xf bank_mask:0xf bound_ctrl:1
	v_pk_mul_f32 v[14:15], v[26:27], v[36:37] op_sel:[1,0] op_sel_hi:[1,1]
	v_pk_fma_f32 v[6:7], v[22:23], v[6:7], v[64:65] op_sel:[0,0,0] op_sel_hi:[0,1,1]
	v_add_f32_dpp v60, v60, v60 quad_perm:[2,3,0,1] row_mask:0xf bank_mask:0xf bound_ctrl:1
	v_add_f32_dpp v62, v63, v62 quad_perm:[1,0,3,2] row_mask:0xf bank_mask:0xf bound_ctrl:1
	v_pk_fma_f32 v[8:9], v[22:23], v[8:9], v[14:15] op_sel:[1,0,0] op_sel_hi:[1,1,1]
	v_add_f32_dpp v60, v60, v60 row_half_mirror row_mask:0xf bank_mask:0xf bound_ctrl:1
	v_add_f32_dpp v62, v62, v62 quad_perm:[2,3,0,1] row_mask:0xf bank_mask:0xf bound_ctrl:1
	ds_read_b128 v[54:57], v250 offset:30208
	v_add_f32_dpp v60, v60, v60 row_mirror row_mask:0xf bank_mask:0xf bound_ctrl:1
	v_add_f32_dpp v62, v62, v62 row_half_mirror row_mask:0xf bank_mask:0xf bound_ctrl:1
	ds_read_b128 v[38:41], v250 offset:29184
	v_mov_b32_dpp v61, v60 quad_perm:[1,0,3,2] row_mask:0xf bank_mask:0xf bound_ctrl:1
	v_add_f32_dpp v62, v62, v62 row_mirror row_mask:0xf bank_mask:0xf bound_ctrl:1
	s_waitcnt lgkmcnt(8)
	v_pk_fma_f32 v[2:3], v[32:33], v[60:61], v[2:3] op_sel:[0,0,0] op_sel_hi:[0,1,1] neg_lo:[0,1,0] neg_hi:[0,1,0]
	v_pk_fma_f32 v[4:5], v[32:33], v[60:61], v[4:5] op_sel:[1,0,0] op_sel_hi:[1,1,1] neg_lo:[0,1,0] neg_hi:[0,1,0]
	v_mov_b32_dpp v63, v62 quad_perm:[1,0,3,2] row_mask:0xf bank_mask:0xf bound_ctrl:1
	v_pk_fma_f32 v[6:7], v[34:35], v[60:61], v[6:7] op_sel:[0,0,0] op_sel_hi:[0,1,1] neg_lo:[0,1,0] neg_hi:[0,1,0]
	v_cvt_pk_bf16_f32 v64, v62, v63
	v_pk_fma_f32 v[8:9], v[34:35], v[60:61], v[8:9] op_sel:[1,0,0] op_sel_hi:[1,1,1] neg_lo:[0,1,0] neg_hi:[0,1,0]
	ds_write_b32 v253, v64 offset:2176
	v_pk_mul_f32 v[62:63], v[16:17], v[2:3] op_sel:[0,0] op_sel_hi:[0,1]
	ds_read_b128 v[28:31], v250 offset:31488
	v_pk_fma_f32 v[62:63], v[16:17], v[4:5], v[62:63] op_sel:[1,0,0] op_sel_hi:[1,1,1]
	ds_read_b32 v36, v251 offset:32000
	v_pk_fma_f32 v[62:63], v[18:19], v[6:7], v[62:63] op_sel:[0,0,0] op_sel_hi:[0,1,1]
	ds_read_b32 v37, v252 offset:32000
	v_pk_fma_f32 v[62:63], v[18:19], v[8:9], v[62:63] op_sel:[1,0,0] op_sel_hi:[1,1,1]
	ds_read_b128 v[24:27], v250 offset:31232
	ds_read_b128 v[20:23], v250 offset:30976
	s_waitcnt lgkmcnt(8)
	v_pk_mul_f32 v[60:61], v[50:51], v[2:3] op_sel:[0,0] op_sel_hi:[0,1]
	v_pk_mul_f32 v[64:65], v[46:47], v[58:59] op_sel:[0,0] op_sel_hi:[0,1]
	v_pk_fma_f32 v[60:61], v[50:51], v[4:5], v[60:61] op_sel:[1,0,0] op_sel_hi:[1,1,1]
	v_pk_mul_f32 v[14:15], v[46:47], v[58:59] op_sel:[1,0] op_sel_hi:[1,1]
	v_pk_fma_f32 v[60:61], v[52:53], v[6:7], v[60:61] op_sel:[0,0,0] op_sel_hi:[0,1,1]
	v_pk_fma_f32 v[2:3], v[42:43], v[2:3], v[64:65] op_sel:[0,0,0] op_sel_hi:[0,1,1]
	v_pk_fma_f32 v[60:61], v[52:53], v[8:9], v[60:61] op_sel:[1,0,0] op_sel_hi:[1,1,1]
	v_pk_fma_f32 v[4:5], v[42:43], v[4:5], v[14:15] op_sel:[1,0,0] op_sel_hi:[1,1,1]
	v_pk_mul_f32 v[64:65], v[48:49], v[58:59] op_sel:[0,0] op_sel_hi:[0,1]
	v_add_f32_dpp v60, v61, v60 quad_perm:[1,0,3,2] row_mask:0xf bank_mask:0xf bound_ctrl:1
	v_pk_mul_f32 v[14:15], v[48:49], v[58:59] op_sel:[1,0] op_sel_hi:[1,1]
	v_pk_fma_f32 v[6:7], v[44:45], v[6:7], v[64:65] op_sel:[0,0,0] op_sel_hi:[0,1,1]
	v_add_f32_dpp v60, v60, v60 quad_perm:[2,3,0,1] row_mask:0xf bank_mask:0xf bound_ctrl:1
	v_add_f32_dpp v62, v63, v62 quad_perm:[1,0,3,2] row_mask:0xf bank_mask:0xf bound_ctrl:1
	v_pk_fma_f32 v[8:9], v[44:45], v[8:9], v[14:15] op_sel:[1,0,0] op_sel_hi:[1,1,1]
	v_add_f32_dpp v60, v60, v60 row_half_mirror row_mask:0xf bank_mask:0xf bound_ctrl:1
	v_add_f32_dpp v62, v62, v62 quad_perm:[2,3,0,1] row_mask:0xf bank_mask:0xf bound_ctrl:1
	ds_read_b128 v[32:35], v250 offset:31744
	v_add_f32_dpp v60, v60, v60 row_mirror row_mask:0xf bank_mask:0xf bound_ctrl:1
	v_add_f32_dpp v62, v62, v62 row_half_mirror row_mask:0xf bank_mask:0xf bound_ctrl:1
	ds_read_b128 v[16:19], v250 offset:30720
	v_mov_b32_dpp v61, v60 quad_perm:[1,0,3,2] row_mask:0xf bank_mask:0xf bound_ctrl:1
	v_add_f32_dpp v62, v62, v62 row_mirror row_mask:0xf bank_mask:0xf bound_ctrl:1
	s_waitcnt lgkmcnt(8)
; #define LAS __attribute__((address_space(3)))
; DI unsigned pk2(float a, float b) { f32x2 v = {a, b}; bf2_t r = __builtin_convertvector(v, bf2_t); return __builtin_bit_cast(unsigned, r); }
; DI f32x2 red16p(f32x2 x) { float a = x.x, b = x.y; red16x2(a, b); return (f32x2){a, b}; }
; DI void scan_bh2(const Args& a, int l, int bh, int halfsel, LAS unsigned char* lds) {
;     ...
;             for (int st = 0; st < T; ++st) {
;                 f32x4 nr4, nd4, nk4, nkk4, nb4; f32x2 nv2;
;                 if (st < T - 1) {
;                     const LAS float* o = cur + (st + 1) * 384;
;                     nr4 = *(const LAS f32x4*)(o + kq * 4); nd4 = *(const LAS f32x4*)(o + 64 + kq * 4); nk4 = *(const LAS f32x4*)(o + 128 + kq * 4);
;                     nkk4 = *(const LAS f32x4*)(o + 192 + kq * 4); nb4 = *(const LAS f32x4*)(o + 256 + kq * 4); nv2 = *(const LAS f32x2*)(o + 320 + row0);
;                 }
;                 f32x2 sa = S[0] * kk4[0]; sa += S[1] * kk4[1]; f32x2 sb = S[2] * kk4[2]; sb += S[3] * kk4[3]; sa += sb;
;                 sa = red16p(sa); sa = -sa;
; #pragma unroll
;                 for (int j = 0; j < 4; ++j) S[j] = S[j] * d4[j] + sa * b4[j] + v2 * k4[j];
;                 f32x2 y = S[0] * r4[0]; y += S[1] * r4[1]; f32x2 yc = S[2] * r4[2]; yc += S[3] * r4[3]; y += yc;
;                 y = red16p(y);
;                 *(LAS unsigned*)(yb + st * 128 + row0 * 2) = pk2(y.x, y.y);
;                 if (st < T - 1) { r4 = nr4; d4 = nd4; k4 = nk4; kk4 = nkk4; b4 = nb4; v2 = nv2; }
	v_pk_fma_f32 v[2:3], v[54:55], v[60:61], v[2:3] op_sel:[0,0,0] op_sel_hi:[0,1,1] neg_lo:[0,1,0] neg_hi:[0,1,0]
	v_pk_fma_f32 v[4:5], v[54:55], v[60:61], v[4:5] op_sel:[1,0,0] op_sel_hi:[1,1,1] neg_lo:[0,1,0] neg_hi:[0,1,0]
	v_mov_b32_dpp v63, v62 quad_perm:[1,0,3,2] row_mask:0xf bank_mask:0xf bound_ctrl:1
	v_pk_fma_f32 v[6:7], v[56:57], v[60:61], v[6:7] op_sel:[0,0,0] op_sel_hi:[0,1,1] neg_lo:[0,1,0] neg_hi:[0,1,0]
	v_cvt_pk_bf16_f32 v64, v62, v63
	v_pk_fma_f32 v[8:9], v[56:57], v[60:61], v[8:9] op_sel:[1,0,0] op_sel_hi:[1,1,1] neg_lo:[0,1,0] neg_hi:[0,1,0]
	ds_write_b32 v253, v64 offset:2304
	v_pk_mul_f32 v[62:63], v[38:39], v[2:3] op_sel:[0,0] op_sel_hi:[0,1]
	ds_read_b128 v[50:53], v250 offset:33024
	v_pk_fma_f32 v[62:63], v[38:39], v[4:5], v[62:63] op_sel:[1,0,0] op_sel_hi:[1,1,1]
	ds_read_b32 v58, v251 offset:33536
	v_pk_fma_f32 v[62:63], v[40:41], v[6:7], v[62:63] op_sel:[0,0,0] op_sel_hi:[0,1,1]
	ds_read_b32 v59, v252 offset:33536
	v_pk_fma_f32 v[62:63], v[40:41], v[8:9], v[62:63] op_sel:[1,0,0] op_sel_hi:[1,1,1]
	ds_read_b128 v[46:49], v250 offset:32768
	ds_read_b128 v[42:45], v250 offset:32512
	s_waitcnt lgkmcnt(8)
	v_pk_mul_f32 v[60:61], v[28:29], v[2:3] op_sel:[0,0] op_sel_hi:[0,1]
	v_pk_mul_f32 v[64:65], v[24:25], v[36:37] op_sel:[0,0] op_sel_hi:[0,1]
	v_pk_fma_f32 v[60:61], v[28:29], v[4:5], v[60:61] op_sel:[1,0,0] op_sel_hi:[1,1,1]
	v_pk_mul_f32 v[14:15], v[24:25], v[36:37] op_sel:[1,0] op_sel_hi:[1,1]
	v_pk_fma_f32 v[60:61], v[30:31], v[6:7], v[60:61] op_sel:[0,0,0] op_sel_hi:[0,1,1]
	v_pk_fma_f32 v[2:3], v[20:21], v[2:3], v[64:65] op_sel:[0,0,0] op_sel_hi:[0,1,1]
	v_pk_fma_f32 v[60:61], v[30:31], v[8:9], v[60:61] op_sel:[1,0,0] op_sel_hi:[1,1,1]
	v_pk_fma_f32 v[4:5], v[20:21], v[4:5], v[14:15] op_sel:[1,0,0] op_sel_hi:[1,1,1]
	v_pk_mul_f32 v[64:65], v[26:27], v[36:37] op_sel:[0,0] op_sel_hi:[0,1]
	v_add_f32_dpp v60, v61, v60 quad_perm:[1,0,3,2] row_mask:0xf bank_mask:0xf bound_ctrl:1
	v_pk_mul_f32 v[14:15], v[26:27], v[36:37] op_sel:[1,0] op_sel_hi:[1,1]
	v_pk_fma_f32 v[6:7], v[22:23], v[6:7], v[64:65] op_sel:[0,0,0] op_sel_hi:[0,1,1]
	v_add_f32_dpp v60, v60, v60 quad_perm:[2,3,0,1] row_mask:0xf bank_mask:0xf bound_ctrl:1
	v_add_f32_dpp v62, v63, v62 quad_perm:[1,0,3,2] row_mask:0xf bank_mask:0xf bound_ctrl:1
	v_pk_fma_f32 v[8:9], v[22:23], v[8:9], v[14:15] op_sel:[1,0,0] op_sel_hi:[1,1,1]
	v_add_f32_dpp v60, v60, v60 row_half_mirror row_mask:0xf bank_mask:0xf bound_ctrl:1
	v_add_f32_dpp v62, v62, v62 quad_perm:[2,3,0,1] row_mask:0xf bank_mask:0xf bound_ctrl:1
	ds_read_b128 v[54:57], v250 offset:33280
	v_add_f32_dpp v60, v60, v60 row_mirror row_mask:0xf bank_mask:0xf bound_ctrl:1
	v_add_f32_dpp v62, v62, v62 row_half_mirror row_mask:0xf bank_mask:0xf bound_ctrl:1
	ds_read_b128 v[38:41], v250 offset:32256
	v_mov_b32_dpp v61, v60 quad_perm:[1,0,3,2] row_mask:0xf bank_mask:0xf bound_ctrl:1
	v_add_f32_dpp v62, v62, v62 row_mirror row_mask:0xf bank_mask:0xf bound_ctrl:1
	s_waitcnt lgkmcnt(8)
	v_pk_fma_f32 v[2:3], v[32:33], v[60:61], v[2:3] op_sel:[0,0,0] op_sel_hi:[0,1,1] neg_lo:[0,1,0] neg_hi:[0,1,0]
	v_pk_fma_f32 v[4:5], v[32:33], v[60:61], v[4:5] op_sel:[1,0,0] op_sel_hi:[1,1,1] neg_lo:[0,1,0] neg_hi:[0,1,0]
	v_mov_b32_dpp v63, v62 quad_perm:[1,0,3,2] row_mask:0xf bank_mask:0xf bound_ctrl:1
	v_pk_fma_f32 v[6:7], v[34:35], v[60:61], v[6:7] op_sel:[0,0,0] op_sel_hi:[0,1,1] neg_lo:[0,1,0] neg_hi:[0,1,0]
	v_cvt_pk_bf16_f32 v64, v62, v63
	v_pk_fma_f32 v[8:9], v[34:35], v[60:61], v[8:9] op_sel:[1,0,0] op_sel_hi:[1,1,1] neg_lo:[0,1,0] neg_hi:[0,1,0]
	ds_write_b32 v253, v64 offset:2432
	v_pk_mul_f32 v[62:63], v[16:17], v[2:3] op_sel:[0,0] op_sel_hi:[0,1]
	ds_read_b128 v[28:31], v250 offset:34560
	v_pk_fma_f32 v[62:63], v[16:17], v[4:5], v[62:63] op_sel:[1,0,0] op_sel_hi:[1,1,1]
	ds_read_b32 v36, v251 offset:35072
	v_pk_fma_f32 v[62:63], v[18:19], v[6:7], v[62:63] op_sel:[0,0,0] op_sel_hi:[0,1,1]
	ds_read_b32 v37, v252 offset:35072
	v_pk_fma_f32 v[62:63], v[18:19], v[8:9], v[62:63] op_sel:[1,0,0] op_sel_hi:[1,1,1]
	ds_read_b128 v[24:27], v250 offset:34304
	ds_read_b128 v[20:23], v250 offset:34048
	s_waitcnt lgkmcnt(8)
	v_pk_mul_f32 v[60:61], v[50:51], v[2:3] op_sel:[0,0] op_sel_hi:[0,1]
	v_pk_mul_f32 v[64:65], v[46:47], v[58:59] op_sel:[0,0] op_sel_hi:[0,1]
	v_pk_fma_f32 v[60:61], v[50:51], v[4:5], v[60:61] op_sel:[1,0,0] op_sel_hi:[1,1,1]
	v_pk_mul_f32 v[14:15], v[46:47], v[58:59] op_sel:[1,0] op_sel_hi:[1,1]
	v_pk_fma_f32 v[60:61], v[52:53], v[6:7], v[60:61] op_sel:[0,0,0] op_sel_hi:[0,1,1]
	v_pk_fma_f32 v[2:3], v[42:43], v[2:3], v[64:65] op_sel:[0,0,0] op_sel_hi:[0,1,1]
	v_pk_fma_f32 v[60:61], v[52:53], v[8:9], v[60:61] op_sel:[1,0,0] op_sel_hi:[1,1,1]
	v_pk_fma_f32 v[4:5], v[42:43], v[4:5], v[14:15] op_sel:[1,0,0] op_sel_hi:[1,1,1]
	v_pk_mul_f32 v[64:65], v[48:49], v[58:59] op_sel:[0,0] op_sel_hi:[0,1]
	v_add_f32_dpp v60, v61, v60 quad_perm:[1,0,3,2] row_mask:0xf bank_mask:0xf bound_ctrl:1
	v_pk_mul_f32 v[14:15], v[48:49], v[58:59] op_sel:[1,0] op_sel_hi:[1,1]
	v_pk_fma_f32 v[6:7], v[44:45], v[6:7], v[64:65] op_sel:[0,0,0] op_sel_hi:[0,1,1]
	v_add_f32_dpp v60, v60, v60 quad_perm:[2,3,0,1] row_mask:0xf bank_mask:0xf bound_ctrl:1
	v_add_f32_dpp v62, v63, v62 quad_perm:[1,0,3,2] row_mask:0xf bank_mask:0xf bound_ctrl:1
	v_pk_fma_f32 v[8:9], v[44:45], v[8:9], v[14:15] op_sel:[1,0,0] op_sel_hi:[1,1,1]
	v_add_f32_dpp v60, v60, v60 row_half_mirror row_mask:0xf bank_mask:0xf bound_ctrl:1
	v_add_f32_dpp v62, v62, v62 quad_perm:[2,3,0,1] row_mask:0xf bank_mask:0xf bound_ctrl:1
	ds_read_b128 v[32:35], v250 offset:34816
	v_add_f32_dpp v60, v60, v60 row_mirror row_mask:0xf bank_mask:0xf bound_ctrl:1
	v_add_f32_dpp v62, v62, v62 row_half_mirror row_mask:0xf bank_mask:0xf bound_ctrl:1
	ds_read_b128 v[16:19], v250 offset:33792
	v_mov_b32_dpp v61, v60 quad_perm:[1,0,3,2] row_mask:0xf bank_mask:0xf bound_ctrl:1
	v_add_f32_dpp v62, v62, v62 row_mirror row_mask:0xf bank_mask:0xf bound_ctrl:1
	s_waitcnt lgkmcnt(8)
; #define LAS __attribute__((address_space(3)))
; DI unsigned pk2(float a, float b) { f32x2 v = {a, b}; bf2_t r = __builtin_convertvector(v, bf2_t); return __builtin_bit_cast(unsigned, r); }
; DI f32x2 red16p(f32x2 x) { float a = x.x, b = x.y; red16x2(a, b); return (f32x2){a, b}; }
; DI void scan_bh2(const Args& a, int l, int bh, int halfsel, LAS unsigned char* lds) {
;     ...
;             for (int st = 0; st < T; ++st) {
;                 f32x4 nr4, nd4, nk4, nkk4, nb4; f32x2 nv2;
;                 if (st < T - 1) {
;                     const LAS float* o = cur + (st + 1) * 384;
;                     nr4 = *(const LAS f32x4*)(o + kq * 4); nd4 = *(const LAS f32x4*)(o + 64 + kq * 4); nk4 = *(const LAS f32x4*)(o + 128 + kq * 4);
;                     nkk4 = *(const LAS f32x4*)(o + 192 + kq * 4); nb4 = *(const LAS f32x4*)(o + 256 + kq * 4); nv2 = *(const LAS f32x2*)(o + 320 + row0);
;                 }
;                 f32x2 sa = S[0] * kk4[0]; sa += S[1] * kk4[1]; f32x2 sb = S[2] * kk4[2]; sb += S[3] * kk4[3]; sa += sb;
;                 sa = red16p(sa); sa = -sa;
; #pragma unroll
;                 for (int j = 0; j < 4; ++j) S[j] = S[j] * d4[j] + sa * b4[j] + v2 * k4[j];
;                 f32x2 y = S[0] * r4[0]; y += S[1] * r4[1]; f32x2 yc = S[2] * r4[2]; yc += S[3] * r4[3]; y += yc;
;                 y = red16p(y);
;                 *(LAS unsigned*)(yb + st * 128 + row0 * 2) = pk2(y.x, y.y);
;                 if (st < T - 1) { r4 = nr4; d4 = nd4; k4 = nk4; kk4 = nkk4; b4 = nb4; v2 = nv2; }
	v_pk_fma_f32 v[2:3], v[54:55], v[60:61], v[2:3] op_sel:[0,0,0] op_sel_hi:[0,1,1] neg_lo:[0,1,0] neg_hi:[0,1,0]
	v_pk_fma_f32 v[4:5], v[54:55], v[60:61], v[4:5] op_sel:[1,0,0] op_sel_hi:[1,1,1] neg_lo:[0,1,0] neg_hi:[0,1,0]
	v_mov_b32_dpp v63, v62 quad_perm:[1,0,3,2] row_mask:0xf bank_mask:0xf bound_ctrl:1
	v_pk_fma_f32 v[6:7], v[56:57], v[60:61], v[6:7] op_sel:[0,0,0] op_sel_hi:[0,1,1] neg_lo:[0,1,0] neg_hi:[0,1,0]
	v_cvt_pk_bf16_f32 v64, v62, v63
	v_pk_fma_f32 v[8:9], v[56:57], v[60:61], v[8:9] op_sel:[1,0,0] op_sel_hi:[1,1,1] neg_lo:[0,1,0] neg_hi:[0,1,0]
	ds_write_b32 v253, v64 offset:2560
	v_pk_mul_f32 v[62:63], v[38:39], v[2:3] op_sel:[0,0] op_sel_hi:[0,1]
	ds_read_b128 v[50:53], v250 offset:36096
	v_pk_fma_f32 v[62:63], v[38:39], v[4:5], v[62:63] op_sel:[1,0,0] op_sel_hi:[1,1,1]
	ds_read_b32 v58, v251 offset:36608
	v_pk_fma_f32 v[62:63], v[40:41], v[6:7], v[62:63] op_sel:[0,0,0] op_sel_hi:[0,1,1]
	ds_read_b32 v59, v252 offset:36608
	v_pk_fma_f32 v[62:63], v[40:41], v[8:9], v[62:63] op_sel:[1,0,0] op_sel_hi:[1,1,1]
	ds_read_b128 v[46:49], v250 offset:35840
	ds_read_b128 v[42:45], v250 offset:35584
	s_waitcnt lgkmcnt(8)
	v_pk_mul_f32 v[60:61], v[28:29], v[2:3] op_sel:[0,0] op_sel_hi:[0,1]
	v_pk_mul_f32 v[64:65], v[24:25], v[36:37] op_sel:[0,0] op_sel_hi:[0,1]
	v_pk_fma_f32 v[60:61], v[28:29], v[4:5], v[60:61] op_sel:[1,0,0] op_sel_hi:[1,1,1]
	v_pk_mul_f32 v[14:15], v[24:25], v[36:37] op_sel:[1,0] op_sel_hi:[1,1]
	v_pk_fma_f32 v[60:61], v[30:31], v[6:7], v[60:61] op_sel:[0,0,0] op_sel_hi:[0,1,1]
	v_pk_fma_f32 v[2:3], v[20:21], v[2:3], v[64:65] op_sel:[0,0,0] op_sel_hi:[0,1,1]
	v_pk_fma_f32 v[60:61], v[30:31], v[8:9], v[60:61] op_sel:[1,0,0] op_sel_hi:[1,1,1]
	v_pk_fma_f32 v[4:5], v[20:21], v[4:5], v[14:15] op_sel:[1,0,0] op_sel_hi:[1,1,1]
	v_pk_mul_f32 v[64:65], v[26:27], v[36:37] op_sel:[0,0] op_sel_hi:[0,1]
	v_add_f32_dpp v60, v61, v60 quad_perm:[1,0,3,2] row_mask:0xf bank_mask:0xf bound_ctrl:1
	v_pk_mul_f32 v[14:15], v[26:27], v[36:37] op_sel:[1,0] op_sel_hi:[1,1]
	v_pk_fma_f32 v[6:7], v[22:23], v[6:7], v[64:65] op_sel:[0,0,0] op_sel_hi:[0,1,1]
	v_add_f32_dpp v60, v60, v60 quad_perm:[2,3,0,1] row_mask:0xf bank_mask:0xf bound_ctrl:1
	v_add_f32_dpp v62, v63, v62 quad_perm:[1,0,3,2] row_mask:0xf bank_mask:0xf bound_ctrl:1
	v_pk_fma_f32 v[8:9], v[22:23], v[8:9], v[14:15] op_sel:[1,0,0] op_sel_hi:[1,1,1]
	v_add_f32_dpp v60, v60, v60 row_half_mirror row_mask:0xf bank_mask:0xf bound_ctrl:1
	v_add_f32_dpp v62, v62, v62 quad_perm:[2,3,0,1] row_mask:0xf bank_mask:0xf bound_ctrl:1
	ds_read_b128 v[54:57], v250 offset:36352
	v_add_f32_dpp v60, v60, v60 row_mirror row_mask:0xf bank_mask:0xf bound_ctrl:1
	v_add_f32_dpp v62, v62, v62 row_half_mirror row_mask:0xf bank_mask:0xf bound_ctrl:1
	ds_read_b128 v[38:41], v250 offset:35328
	v_mov_b32_dpp v61, v60 quad_perm:[1,0,3,2] row_mask:0xf bank_mask:0xf bound_ctrl:1
	v_add_f32_dpp v62, v62, v62 row_mirror row_mask:0xf bank_mask:0xf bound_ctrl:1
	s_waitcnt lgkmcnt(8)
	v_pk_fma_f32 v[2:3], v[32:33], v[60:61], v[2:3] op_sel:[0,0,0] op_sel_hi:[0,1,1] neg_lo:[0,1,0] neg_hi:[0,1,0]
	v_pk_fma_f32 v[4:5], v[32:33], v[60:61], v[4:5] op_sel:[1,0,0] op_sel_hi:[1,1,1] neg_lo:[0,1,0] neg_hi:[0,1,0]
	v_mov_b32_dpp v63, v62 quad_perm:[1,0,3,2] row_mask:0xf bank_mask:0xf bound_ctrl:1
	v_pk_fma_f32 v[6:7], v[34:35], v[60:61], v[6:7] op_sel:[0,0,0] op_sel_hi:[0,1,1] neg_lo:[0,1,0] neg_hi:[0,1,0]
	v_cvt_pk_bf16_f32 v64, v62, v63
	v_pk_fma_f32 v[8:9], v[34:35], v[60:61], v[8:9] op_sel:[1,0,0] op_sel_hi:[1,1,1] neg_lo:[0,1,0] neg_hi:[0,1,0]
	ds_write_b32 v253, v64 offset:2688
	v_pk_mul_f32 v[62:63], v[16:17], v[2:3] op_sel:[0,0] op_sel_hi:[0,1]
	ds_read_b128 v[28:31], v250 offset:37632
	v_pk_fma_f32 v[62:63], v[16:17], v[4:5], v[62:63] op_sel:[1,0,0] op_sel_hi:[1,1,1]
	ds_read_b32 v36, v251 offset:38144
	v_pk_fma_f32 v[62:63], v[18:19], v[6:7], v[62:63] op_sel:[0,0,0] op_sel_hi:[0,1,1]
	ds_read_b32 v37, v252 offset:38144
	v_pk_fma_f32 v[62:63], v[18:19], v[8:9], v[62:63] op_sel:[1,0,0] op_sel_hi:[1,1,1]
	ds_read_b128 v[24:27], v250 offset:37376
	ds_read_b128 v[20:23], v250 offset:37120
	s_waitcnt lgkmcnt(8)
	v_pk_mul_f32 v[60:61], v[50:51], v[2:3] op_sel:[0,0] op_sel_hi:[0,1]
	v_pk_mul_f32 v[64:65], v[46:47], v[58:59] op_sel:[0,0] op_sel_hi:[0,1]
	v_pk_fma_f32 v[60:61], v[50:51], v[4:5], v[60:61] op_sel:[1,0,0] op_sel_hi:[1,1,1]
	v_pk_mul_f32 v[14:15], v[46:47], v[58:59] op_sel:[1,0] op_sel_hi:[1,1]
	v_pk_fma_f32 v[60:61], v[52:53], v[6:7], v[60:61] op_sel:[0,0,0] op_sel_hi:[0,1,1]
	v_pk_fma_f32 v[2:3], v[42:43], v[2:3], v[64:65] op_sel:[0,0,0] op_sel_hi:[0,1,1]
	v_pk_fma_f32 v[60:61], v[52:53], v[8:9], v[60:61] op_sel:[1,0,0] op_sel_hi:[1,1,1]
	v_pk_fma_f32 v[4:5], v[42:43], v[4:5], v[14:15] op_sel:[1,0,0] op_sel_hi:[1,1,1]
	v_pk_mul_f32 v[64:65], v[48:49], v[58:59] op_sel:[0,0] op_sel_hi:[0,1]
	v_add_f32_dpp v60, v61, v60 quad_perm:[1,0,3,2] row_mask:0xf bank_mask:0xf bound_ctrl:1
	v_pk_mul_f32 v[14:15], v[48:49], v[58:59] op_sel:[1,0] op_sel_hi:[1,1]
	v_pk_fma_f32 v[6:7], v[44:45], v[6:7], v[64:65] op_sel:[0,0,0] op_sel_hi:[0,1,1]
	v_add_f32_dpp v60, v60, v60 quad_perm:[2,3,0,1] row_mask:0xf bank_mask:0xf bound_ctrl:1
	v_add_f32_dpp v62, v63, v62 quad_perm:[1,0,3,2] row_mask:0xf bank_mask:0xf bound_ctrl:1
	v_pk_fma_f32 v[8:9], v[44:45], v[8:9], v[14:15] op_sel:[1,0,0] op_sel_hi:[1,1,1]
	v_add_f32_dpp v60, v60, v60 row_half_mirror row_mask:0xf bank_mask:0xf bound_ctrl:1
	v_add_f32_dpp v62, v62, v62 quad_perm:[2,3,0,1] row_mask:0xf bank_mask:0xf bound_ctrl:1
	ds_read_b128 v[32:35], v250 offset:37888
	v_add_f32_dpp v60, v60, v60 row_mirror row_mask:0xf bank_mask:0xf bound_ctrl:1
	v_add_f32_dpp v62, v62, v62 row_half_mirror row_mask:0xf bank_mask:0xf bound_ctrl:1
	ds_read_b128 v[16:19], v250 offset:36864
	v_mov_b32_dpp v61, v60 quad_perm:[1,0,3,2] row_mask:0xf bank_mask:0xf bound_ctrl:1
	v_add_f32_dpp v62, v62, v62 row_mirror row_mask:0xf bank_mask:0xf bound_ctrl:1
	s_waitcnt lgkmcnt(8)
; #define LAS __attribute__((address_space(3)))
; DI unsigned pk2(float a, float b) { f32x2 v = {a, b}; bf2_t r = __builtin_convertvector(v, bf2_t); return __builtin_bit_cast(unsigned, r); }
; DI f32x2 red16p(f32x2 x) { float a = x.x, b = x.y; red16x2(a, b); return (f32x2){a, b}; }
; DI void scan_bh2(const Args& a, int l, int bh, int halfsel, LAS unsigned char* lds) {
;     ...
;             for (int st = 0; st < T; ++st) {
;                 f32x4 nr4, nd4, nk4, nkk4, nb4; f32x2 nv2;
;                 if (st < T - 1) {
;                     const LAS float* o = cur + (st + 1) * 384;
;                     nr4 = *(const LAS f32x4*)(o + kq * 4); nd4 = *(const LAS f32x4*)(o + 64 + kq * 4); nk4 = *(const LAS f32x4*)(o + 128 + kq * 4);
;                     nkk4 = *(const LAS f32x4*)(o + 192 + kq * 4); nb4 = *(const LAS f32x4*)(o + 256 + kq * 4); nv2 = *(const LAS f32x2*)(o + 320 + row0);
;                 }
;                 f32x2 sa = S[0] * kk4[0]; sa += S[1] * kk4[1]; f32x2 sb = S[2] * kk4[2]; sb += S[3] * kk4[3]; sa += sb;
;                 sa = red16p(sa); sa = -sa;
; #pragma unroll
;                 for (int j = 0; j < 4; ++j) S[j] = S[j] * d4[j] + sa * b4[j] + v2 * k4[j];
;                 f32x2 y = S[0] * r4[0]; y += S[1] * r4[1]; f32x2 yc = S[2] * r4[2]; yc += S[3] * r4[3]; y += yc;
;                 y = red16p(y);
;                 *(LAS unsigned*)(yb + st * 128 + row0 * 2) = pk2(y.x, y.y);
;                 if (st < T - 1) { r4 = nr4; d4 = nd4; k4 = nk4; kk4 = nkk4; b4 = nb4; v2 = nv2; }
	v_pk_fma_f32 v[2:3], v[54:55], v[60:61], v[2:3] op_sel:[0,0,0] op_sel_hi:[0,1,1] neg_lo:[0,1,0] neg_hi:[0,1,0]
	v_pk_fma_f32 v[4:5], v[54:55], v[60:61], v[4:5] op_sel:[1,0,0] op_sel_hi:[1,1,1] neg_lo:[0,1,0] neg_hi:[0,1,0]
	v_mov_b32_dpp v63, v62 quad_perm:[1,0,3,2] row_mask:0xf bank_mask:0xf bound_ctrl:1
	v_pk_fma_f32 v[6:7], v[56:57], v[60:61], v[6:7] op_sel:[0,0,0] op_sel_hi:[0,1,1] neg_lo:[0,1,0] neg_hi:[0,1,0]
	v_cvt_pk_bf16_f32 v64, v62, v63
	v_pk_fma_f32 v[8:9], v[56:57], v[60:61], v[8:9] op_sel:[1,0,0] op_sel_hi:[1,1,1] neg_lo:[0,1,0] neg_hi:[0,1,0]
	ds_write_b32 v253, v64 offset:2816
	v_pk_mul_f32 v[62:63], v[38:39], v[2:3] op_sel:[0,0] op_sel_hi:[0,1]
	ds_read_b128 v[50:53], v250 offset:39168
	v_pk_fma_f32 v[62:63], v[38:39], v[4:5], v[62:63] op_sel:[1,0,0] op_sel_hi:[1,1,1]
	ds_read_b32 v58, v251 offset:39680
	v_pk_fma_f32 v[62:63], v[40:41], v[6:7], v[62:63] op_sel:[0,0,0] op_sel_hi:[0,1,1]
	ds_read_b32 v59, v252 offset:39680
	v_pk_fma_f32 v[62:63], v[40:41], v[8:9], v[62:63] op_sel:[1,0,0] op_sel_hi:[1,1,1]
	ds_read_b128 v[46:49], v250 offset:38912
	ds_read_b128 v[42:45], v250 offset:38656
	s_waitcnt lgkmcnt(8)
	v_pk_mul_f32 v[60:61], v[28:29], v[2:3] op_sel:[0,0] op_sel_hi:[0,1]
	v_pk_mul_f32 v[64:65], v[24:25], v[36:37] op_sel:[0,0] op_sel_hi:[0,1]
	v_pk_fma_f32 v[60:61], v[28:29], v[4:5], v[60:61] op_sel:[1,0,0] op_sel_hi:[1,1,1]
	v_pk_mul_f32 v[14:15], v[24:25], v[36:37] op_sel:[1,0] op_sel_hi:[1,1]
	v_pk_fma_f32 v[60:61], v[30:31], v[6:7], v[60:61] op_sel:[0,0,0] op_sel_hi:[0,1,1]
	v_pk_fma_f32 v[2:3], v[20:21], v[2:3], v[64:65] op_sel:[0,0,0] op_sel_hi:[0,1,1]
	v_pk_fma_f32 v[60:61], v[30:31], v[8:9], v[60:61] op_sel:[1,0,0] op_sel_hi:[1,1,1]
	v_pk_fma_f32 v[4:5], v[20:21], v[4:5], v[14:15] op_sel:[1,0,0] op_sel_hi:[1,1,1]
	v_pk_mul_f32 v[64:65], v[26:27], v[36:37] op_sel:[0,0] op_sel_hi:[0,1]
	v_add_f32_dpp v60, v61, v60 quad_perm:[1,0,3,2] row_mask:0xf bank_mask:0xf bound_ctrl:1
	v_pk_mul_f32 v[14:15], v[26:27], v[36:37] op_sel:[1,0] op_sel_hi:[1,1]
	v_pk_fma_f32 v[6:7], v[22:23], v[6:7], v[64:65] op_sel:[0,0,0] op_sel_hi:[0,1,1]
	v_add_f32_dpp v60, v60, v60 quad_perm:[2,3,0,1] row_mask:0xf bank_mask:0xf bound_ctrl:1
	v_add_f32_dpp v62, v63, v62 quad_perm:[1,0,3,2] row_mask:0xf bank_mask:0xf bound_ctrl:1
	v_pk_fma_f32 v[8:9], v[22:23], v[8:9], v[14:15] op_sel:[1,0,0] op_sel_hi:[1,1,1]
	v_add_f32_dpp v60, v60, v60 row_half_mirror row_mask:0xf bank_mask:0xf bound_ctrl:1
	v_add_f32_dpp v62, v62, v62 quad_perm:[2,3,0,1] row_mask:0xf bank_mask:0xf bound_ctrl:1
	ds_read_b128 v[54:57], v250 offset:39424
	v_add_f32_dpp v60, v60, v60 row_mirror row_mask:0xf bank_mask:0xf bound_ctrl:1
	v_add_f32_dpp v62, v62, v62 row_half_mirror row_mask:0xf bank_mask:0xf bound_ctrl:1
	ds_read_b128 v[38:41], v250 offset:38400
	v_mov_b32_dpp v61, v60 quad_perm:[1,0,3,2] row_mask:0xf bank_mask:0xf bound_ctrl:1
	v_add_f32_dpp v62, v62, v62 row_mirror row_mask:0xf bank_mask:0xf bound_ctrl:1
	s_waitcnt lgkmcnt(8)
	v_pk_fma_f32 v[2:3], v[32:33], v[60:61], v[2:3] op_sel:[0,0,0] op_sel_hi:[0,1,1] neg_lo:[0,1,0] neg_hi:[0,1,0]
	v_pk_fma_f32 v[4:5], v[32:33], v[60:61], v[4:5] op_sel:[1,0,0] op_sel_hi:[1,1,1] neg_lo:[0,1,0] neg_hi:[0,1,0]
	v_mov_b32_dpp v63, v62 quad_perm:[1,0,3,2] row_mask:0xf bank_mask:0xf bound_ctrl:1
	v_pk_fma_f32 v[6:7], v[34:35], v[60:61], v[6:7] op_sel:[0,0,0] op_sel_hi:[0,1,1] neg_lo:[0,1,0] neg_hi:[0,1,0]
	v_cvt_pk_bf16_f32 v64, v62, v63
	v_pk_fma_f32 v[8:9], v[34:35], v[60:61], v[8:9] op_sel:[1,0,0] op_sel_hi:[1,1,1] neg_lo:[0,1,0] neg_hi:[0,1,0]
	ds_write_b32 v253, v64 offset:2944
	v_pk_mul_f32 v[62:63], v[16:17], v[2:3] op_sel:[0,0] op_sel_hi:[0,1]
	ds_read_b128 v[28:31], v250 offset:40704
	v_pk_fma_f32 v[62:63], v[16:17], v[4:5], v[62:63] op_sel:[1,0,0] op_sel_hi:[1,1,1]
	ds_read_b32 v36, v251 offset:41216
	v_pk_fma_f32 v[62:63], v[18:19], v[6:7], v[62:63] op_sel:[0,0,0] op_sel_hi:[0,1,1]
	ds_read_b32 v37, v252 offset:41216
	v_pk_fma_f32 v[62:63], v[18:19], v[8:9], v[62:63] op_sel:[1,0,0] op_sel_hi:[1,1,1]
	ds_read_b128 v[24:27], v250 offset:40448
	ds_read_b128 v[20:23], v250 offset:40192
	s_waitcnt lgkmcnt(8)
	v_pk_mul_f32 v[60:61], v[50:51], v[2:3] op_sel:[0,0] op_sel_hi:[0,1]
	v_pk_mul_f32 v[64:65], v[46:47], v[58:59] op_sel:[0,0] op_sel_hi:[0,1]
	v_pk_fma_f32 v[60:61], v[50:51], v[4:5], v[60:61] op_sel:[1,0,0] op_sel_hi:[1,1,1]
	v_pk_mul_f32 v[14:15], v[46:47], v[58:59] op_sel:[1,0] op_sel_hi:[1,1]
	v_pk_fma_f32 v[60:61], v[52:53], v[6:7], v[60:61] op_sel:[0,0,0] op_sel_hi:[0,1,1]
	v_pk_fma_f32 v[2:3], v[42:43], v[2:3], v[64:65] op_sel:[0,0,0] op_sel_hi:[0,1,1]
	v_pk_fma_f32 v[60:61], v[52:53], v[8:9], v[60:61] op_sel:[1,0,0] op_sel_hi:[1,1,1]
	v_pk_fma_f32 v[4:5], v[42:43], v[4:5], v[14:15] op_sel:[1,0,0] op_sel_hi:[1,1,1]
	v_pk_mul_f32 v[64:65], v[48:49], v[58:59] op_sel:[0,0] op_sel_hi:[0,1]
	v_add_f32_dpp v60, v61, v60 quad_perm:[1,0,3,2] row_mask:0xf bank_mask:0xf bound_ctrl:1
	v_pk_mul_f32 v[14:15], v[48:49], v[58:59] op_sel:[1,0] op_sel_hi:[1,1]
	v_pk_fma_f32 v[6:7], v[44:45], v[6:7], v[64:65] op_sel:[0,0,0] op_sel_hi:[0,1,1]
	v_add_f32_dpp v60, v60, v60 quad_perm:[2,3,0,1] row_mask:0xf bank_mask:0xf bound_ctrl:1
	v_add_f32_dpp v62, v63, v62 quad_perm:[1,0,3,2] row_mask:0xf bank_mask:0xf bound_ctrl:1
	v_pk_fma_f32 v[8:9], v[44:45], v[8:9], v[14:15] op_sel:[1,0,0] op_sel_hi:[1,1,1]
	v_add_f32_dpp v60, v60, v60 row_half_mirror row_mask:0xf bank_mask:0xf bound_ctrl:1
	v_add_f32_dpp v62, v62, v62 quad_perm:[2,3,0,1] row_mask:0xf bank_mask:0xf bound_ctrl:1
	ds_read_b128 v[32:35], v250 offset:40960
	v_add_f32_dpp v60, v60, v60 row_mirror row_mask:0xf bank_mask:0xf bound_ctrl:1
	v_add_f32_dpp v62, v62, v62 row_half_mirror row_mask:0xf bank_mask:0xf bound_ctrl:1
	ds_read_b128 v[16:19], v250 offset:39936
	v_mov_b32_dpp v61, v60 quad_perm:[1,0,3,2] row_mask:0xf bank_mask:0xf bound_ctrl:1
	v_add_f32_dpp v62, v62, v62 row_mirror row_mask:0xf bank_mask:0xf bound_ctrl:1
	s_waitcnt lgkmcnt(8)
; #define LAS __attribute__((address_space(3)))
; DI unsigned pk2(float a, float b) { f32x2 v = {a, b}; bf2_t r = __builtin_convertvector(v, bf2_t); return __builtin_bit_cast(unsigned, r); }
; DI f32x2 red16p(f32x2 x) { float a = x.x, b = x.y; red16x2(a, b); return (f32x2){a, b}; }
; DI void scan_bh2(const Args& a, int l, int bh, int halfsel, LAS unsigned char* lds) {
;     ...
;             for (int st = 0; st < T; ++st) {
;                 f32x4 nr4, nd4, nk4, nkk4, nb4; f32x2 nv2;
;                 if (st < T - 1) {
;                     const LAS float* o = cur + (st + 1) * 384;
;                     nr4 = *(const LAS f32x4*)(o + kq * 4); nd4 = *(const LAS f32x4*)(o + 64 + kq * 4); nk4 = *(const LAS f32x4*)(o + 128 + kq * 4);
;                     nkk4 = *(const LAS f32x4*)(o + 192 + kq * 4); nb4 = *(const LAS f32x4*)(o + 256 + kq * 4); nv2 = *(const LAS f32x2*)(o + 320 + row0);
;                 }
;                 f32x2 sa = S[0] * kk4[0]; sa += S[1] * kk4[1]; f32x2 sb = S[2] * kk4[2]; sb += S[3] * kk4[3]; sa += sb;
;                 sa = red16p(sa); sa = -sa;
; #pragma unroll
;                 for (int j = 0; j < 4; ++j) S[j] = S[j] * d4[j] + sa * b4[j] + v2 * k4[j];
;                 f32x2 y = S[0] * r4[0]; y += S[1] * r4[1]; f32x2 yc = S[2] * r4[2]; yc += S[3] * r4[3]; y += yc;
;                 y = red16p(y);
;                 *(LAS unsigned*)(yb + st * 128 + row0 * 2) = pk2(y.x, y.y);
;                 if (st < T - 1) { r4 = nr4; d4 = nd4; k4 = nk4; kk4 = nkk4; b4 = nb4; v2 = nv2; }
	v_pk_fma_f32 v[2:3], v[54:55], v[60:61], v[2:3] op_sel:[0,0,0] op_sel_hi:[0,1,1] neg_lo:[0,1,0] neg_hi:[0,1,0]
	v_pk_fma_f32 v[4:5], v[54:55], v[60:61], v[4:5] op_sel:[1,0,0] op_sel_hi:[1,1,1] neg_lo:[0,1,0] neg_hi:[0,1,0]
	v_mov_b32_dpp v63, v62 quad_perm:[1,0,3,2] row_mask:0xf bank_mask:0xf bound_ctrl:1
	v_pk_fma_f32 v[6:7], v[56:57], v[60:61], v[6:7] op_sel:[0,0,0] op_sel_hi:[0,1,1] neg_lo:[0,1,0] neg_hi:[0,1,0]
	v_cvt_pk_bf16_f32 v64, v62, v63
	v_pk_fma_f32 v[8:9], v[56:57], v[60:61], v[8:9] op_sel:[1,0,0] op_sel_hi:[1,1,1] neg_lo:[0,1,0] neg_hi:[0,1,0]
	ds_write_b32 v253, v64 offset:3072
	v_pk_mul_f32 v[62:63], v[38:39], v[2:3] op_sel:[0,0] op_sel_hi:[0,1]
	ds_read_b128 v[50:53], v250 offset:42240
	v_pk_fma_f32 v[62:63], v[38:39], v[4:5], v[62:63] op_sel:[1,0,0] op_sel_hi:[1,1,1]
	ds_read_b32 v58, v251 offset:42752
	v_pk_fma_f32 v[62:63], v[40:41], v[6:7], v[62:63] op_sel:[0,0,0] op_sel_hi:[0,1,1]
	ds_read_b32 v59, v252 offset:42752
	v_pk_fma_f32 v[62:63], v[40:41], v[8:9], v[62:63] op_sel:[1,0,0] op_sel_hi:[1,1,1]
	ds_read_b128 v[46:49], v250 offset:41984
	ds_read_b128 v[42:45], v250 offset:41728
	s_waitcnt lgkmcnt(8)
	v_pk_mul_f32 v[60:61], v[28:29], v[2:3] op_sel:[0,0] op_sel_hi:[0,1]
	v_pk_mul_f32 v[64:65], v[24:25], v[36:37] op_sel:[0,0] op_sel_hi:[0,1]
	v_pk_fma_f32 v[60:61], v[28:29], v[4:5], v[60:61] op_sel:[1,0,0] op_sel_hi:[1,1,1]
	v_pk_mul_f32 v[14:15], v[24:25], v[36:37] op_sel:[1,0] op_sel_hi:[1,1]
	v_pk_fma_f32 v[60:61], v[30:31], v[6:7], v[60:61] op_sel:[0,0,0] op_sel_hi:[0,1,1]
	v_pk_fma_f32 v[2:3], v[20:21], v[2:3], v[64:65] op_sel:[0,0,0] op_sel_hi:[0,1,1]
	v_pk_fma_f32 v[60:61], v[30:31], v[8:9], v[60:61] op_sel:[1,0,0] op_sel_hi:[1,1,1]
	v_pk_fma_f32 v[4:5], v[20:21], v[4:5], v[14:15] op_sel:[1,0,0] op_sel_hi:[1,1,1]
	v_pk_mul_f32 v[64:65], v[26:27], v[36:37] op_sel:[0,0] op_sel_hi:[0,1]
	v_add_f32_dpp v60, v61, v60 quad_perm:[1,0,3,2] row_mask:0xf bank_mask:0xf bound_ctrl:1
	v_pk_mul_f32 v[14:15], v[26:27], v[36:37] op_sel:[1,0] op_sel_hi:[1,1]
	v_pk_fma_f32 v[6:7], v[22:23], v[6:7], v[64:65] op_sel:[0,0,0] op_sel_hi:[0,1,1]
	v_add_f32_dpp v60, v60, v60 quad_perm:[2,3,0,1] row_mask:0xf bank_mask:0xf bound_ctrl:1
	v_add_f32_dpp v62, v63, v62 quad_perm:[1,0,3,2] row_mask:0xf bank_mask:0xf bound_ctrl:1
	v_pk_fma_f32 v[8:9], v[22:23], v[8:9], v[14:15] op_sel:[1,0,0] op_sel_hi:[1,1,1]
	v_add_f32_dpp v60, v60, v60 row_half_mirror row_mask:0xf bank_mask:0xf bound_ctrl:1
	v_add_f32_dpp v62, v62, v62 quad_perm:[2,3,0,1] row_mask:0xf bank_mask:0xf bound_ctrl:1
	ds_read_b128 v[54:57], v250 offset:42496
	v_add_f32_dpp v60, v60, v60 row_mirror row_mask:0xf bank_mask:0xf bound_ctrl:1
	v_add_f32_dpp v62, v62, v62 row_half_mirror row_mask:0xf bank_mask:0xf bound_ctrl:1
	ds_read_b128 v[38:41], v250 offset:41472
	v_mov_b32_dpp v61, v60 quad_perm:[1,0,3,2] row_mask:0xf bank_mask:0xf bound_ctrl:1
	v_add_f32_dpp v62, v62, v62 row_mirror row_mask:0xf bank_mask:0xf bound_ctrl:1
	s_waitcnt lgkmcnt(8)
	v_pk_fma_f32 v[2:3], v[32:33], v[60:61], v[2:3] op_sel:[0,0,0] op_sel_hi:[0,1,1] neg_lo:[0,1,0] neg_hi:[0,1,0]
	v_pk_fma_f32 v[4:5], v[32:33], v[60:61], v[4:5] op_sel:[1,0,0] op_sel_hi:[1,1,1] neg_lo:[0,1,0] neg_hi:[0,1,0]
	v_mov_b32_dpp v63, v62 quad_perm:[1,0,3,2] row_mask:0xf bank_mask:0xf bound_ctrl:1
	v_pk_fma_f32 v[6:7], v[34:35], v[60:61], v[6:7] op_sel:[0,0,0] op_sel_hi:[0,1,1] neg_lo:[0,1,0] neg_hi:[0,1,0]
	v_cvt_pk_bf16_f32 v64, v62, v63
	v_pk_fma_f32 v[8:9], v[34:35], v[60:61], v[8:9] op_sel:[1,0,0] op_sel_hi:[1,1,1] neg_lo:[0,1,0] neg_hi:[0,1,0]
	ds_write_b32 v253, v64 offset:3200
	v_pk_mul_f32 v[62:63], v[16:17], v[2:3] op_sel:[0,0] op_sel_hi:[0,1]
	ds_read_b128 v[28:31], v250 offset:43776
	v_pk_fma_f32 v[62:63], v[16:17], v[4:5], v[62:63] op_sel:[1,0,0] op_sel_hi:[1,1,1]
	ds_read_b32 v36, v251 offset:44288
	v_pk_fma_f32 v[62:63], v[18:19], v[6:7], v[62:63] op_sel:[0,0,0] op_sel_hi:[0,1,1]
	ds_read_b32 v37, v252 offset:44288
	v_pk_fma_f32 v[62:63], v[18:19], v[8:9], v[62:63] op_sel:[1,0,0] op_sel_hi:[1,1,1]
	ds_read_b128 v[24:27], v250 offset:43520
	ds_read_b128 v[20:23], v250 offset:43264
	s_waitcnt lgkmcnt(8)
	v_pk_mul_f32 v[60:61], v[50:51], v[2:3] op_sel:[0,0] op_sel_hi:[0,1]
	v_pk_mul_f32 v[64:65], v[46:47], v[58:59] op_sel:[0,0] op_sel_hi:[0,1]
	v_pk_fma_f32 v[60:61], v[50:51], v[4:5], v[60:61] op_sel:[1,0,0] op_sel_hi:[1,1,1]
	v_pk_mul_f32 v[14:15], v[46:47], v[58:59] op_sel:[1,0] op_sel_hi:[1,1]
	v_pk_fma_f32 v[60:61], v[52:53], v[6:7], v[60:61] op_sel:[0,0,0] op_sel_hi:[0,1,1]
	v_pk_fma_f32 v[2:3], v[42:43], v[2:3], v[64:65] op_sel:[0,0,0] op_sel_hi:[0,1,1]
	v_pk_fma_f32 v[60:61], v[52:53], v[8:9], v[60:61] op_sel:[1,0,0] op_sel_hi:[1,1,1]
	v_pk_fma_f32 v[4:5], v[42:43], v[4:5], v[14:15] op_sel:[1,0,0] op_sel_hi:[1,1,1]
	v_pk_mul_f32 v[64:65], v[48:49], v[58:59] op_sel:[0,0] op_sel_hi:[0,1]
	v_add_f32_dpp v60, v61, v60 quad_perm:[1,0,3,2] row_mask:0xf bank_mask:0xf bound_ctrl:1
	v_pk_mul_f32 v[14:15], v[48:49], v[58:59] op_sel:[1,0] op_sel_hi:[1,1]
	v_pk_fma_f32 v[6:7], v[44:45], v[6:7], v[64:65] op_sel:[0,0,0] op_sel_hi:[0,1,1]
	v_add_f32_dpp v60, v60, v60 quad_perm:[2,3,0,1] row_mask:0xf bank_mask:0xf bound_ctrl:1
	v_add_f32_dpp v62, v63, v62 quad_perm:[1,0,3,2] row_mask:0xf bank_mask:0xf bound_ctrl:1
	v_pk_fma_f32 v[8:9], v[44:45], v[8:9], v[14:15] op_sel:[1,0,0] op_sel_hi:[1,1,1]
	v_add_f32_dpp v60, v60, v60 row_half_mirror row_mask:0xf bank_mask:0xf bound_ctrl:1
	v_add_f32_dpp v62, v62, v62 quad_perm:[2,3,0,1] row_mask:0xf bank_mask:0xf bound_ctrl:1
	ds_read_b128 v[32:35], v250 offset:44032
	v_add_f32_dpp v60, v60, v60 row_mirror row_mask:0xf bank_mask:0xf bound_ctrl:1
	v_add_f32_dpp v62, v62, v62 row_half_mirror row_mask:0xf bank_mask:0xf bound_ctrl:1
	ds_read_b128 v[16:19], v250 offset:43008
	v_mov_b32_dpp v61, v60 quad_perm:[1,0,3,2] row_mask:0xf bank_mask:0xf bound_ctrl:1
	v_add_f32_dpp v62, v62, v62 row_mirror row_mask:0xf bank_mask:0xf bound_ctrl:1
	s_waitcnt lgkmcnt(8)
; #define LAS __attribute__((address_space(3)))
; DI unsigned pk2(float a, float b) { f32x2 v = {a, b}; bf2_t r = __builtin_convertvector(v, bf2_t); return __builtin_bit_cast(unsigned, r); }
; DI f32x2 red16p(f32x2 x) { float a = x.x, b = x.y; red16x2(a, b); return (f32x2){a, b}; }
; DI void scan_bh2(const Args& a, int l, int bh, int halfsel, LAS unsigned char* lds) {
;     ...
;             for (int st = 0; st < T; ++st) {
;                 f32x4 nr4, nd4, nk4, nkk4, nb4; f32x2 nv2;
;                 if (st < T - 1) {
;                     const LAS float* o = cur + (st + 1) * 384;
;                     nr4 = *(const LAS f32x4*)(o + kq * 4); nd4 = *(const LAS f32x4*)(o + 64 + kq * 4); nk4 = *(const LAS f32x4*)(o + 128 + kq * 4);
;                     nkk4 = *(const LAS f32x4*)(o + 192 + kq * 4); nb4 = *(const LAS f32x4*)(o + 256 + kq * 4); nv2 = *(const LAS f32x2*)(o + 320 + row0);
;                 }
;                 f32x2 sa = S[0] * kk4[0]; sa += S[1] * kk4[1]; f32x2 sb = S[2] * kk4[2]; sb += S[3] * kk4[3]; sa += sb;
;                 sa = red16p(sa); sa = -sa;
; #pragma unroll
;                 for (int j = 0; j < 4; ++j) S[j] = S[j] * d4[j] + sa * b4[j] + v2 * k4[j];
;                 f32x2 y = S[0] * r4[0]; y += S[1] * r4[1]; f32x2 yc = S[2] * r4[2]; yc += S[3] * r4[3]; y += yc;
;                 y = red16p(y);
;                 *(LAS unsigned*)(yb + st * 128 + row0 * 2) = pk2(y.x, y.y);
;                 if (st < T - 1) { r4 = nr4; d4 = nd4; k4 = nk4; kk4 = nkk4; b4 = nb4; v2 = nv2; }
	v_pk_fma_f32 v[2:3], v[54:55], v[60:61], v[2:3] op_sel:[0,0,0] op_sel_hi:[0,1,1] neg_lo:[0,1,0] neg_hi:[0,1,0]
	v_pk_fma_f32 v[4:5], v[54:55], v[60:61], v[4:5] op_sel:[1,0,0] op_sel_hi:[1,1,1] neg_lo:[0,1,0] neg_hi:[0,1,0]
	v_mov_b32_dpp v63, v62 quad_perm:[1,0,3,2] row_mask:0xf bank_mask:0xf bound_ctrl:1
	v_pk_fma_f32 v[6:7], v[56:57], v[60:61], v[6:7] op_sel:[0,0,0] op_sel_hi:[0,1,1] neg_lo:[0,1,0] neg_hi:[0,1,0]
	v_cvt_pk_bf16_f32 v64, v62, v63
	v_pk_fma_f32 v[8:9], v[56:57], v[60:61], v[8:9] op_sel:[1,0,0] op_sel_hi:[1,1,1] neg_lo:[0,1,0] neg_hi:[0,1,0]
	ds_write_b32 v253, v64 offset:3328
	v_pk_mul_f32 v[62:63], v[38:39], v[2:3] op_sel:[0,0] op_sel_hi:[0,1]
	ds_read_b128 v[50:53], v250 offset:45312
	v_pk_fma_f32 v[62:63], v[38:39], v[4:5], v[62:63] op_sel:[1,0,0] op_sel_hi:[1,1,1]
	ds_read_b32 v58, v251 offset:45824
	v_pk_fma_f32 v[62:63], v[40:41], v[6:7], v[62:63] op_sel:[0,0,0] op_sel_hi:[0,1,1]
	ds_read_b32 v59, v252 offset:45824
	v_pk_fma_f32 v[62:63], v[40:41], v[8:9], v[62:63] op_sel:[1,0,0] op_sel_hi:[1,1,1]
	ds_read_b128 v[46:49], v250 offset:45056
	ds_read_b128 v[42:45], v250 offset:44800
	s_waitcnt lgkmcnt(8)
	v_pk_mul_f32 v[60:61], v[28:29], v[2:3] op_sel:[0,0] op_sel_hi:[0,1]
	v_pk_mul_f32 v[64:65], v[24:25], v[36:37] op_sel:[0,0] op_sel_hi:[0,1]
	v_pk_fma_f32 v[60:61], v[28:29], v[4:5], v[60:61] op_sel:[1,0,0] op_sel_hi:[1,1,1]
	v_pk_mul_f32 v[14:15], v[24:25], v[36:37] op_sel:[1,0] op_sel_hi:[1,1]
	v_pk_fma_f32 v[60:61], v[30:31], v[6:7], v[60:61] op_sel:[0,0,0] op_sel_hi:[0,1,1]
	v_pk_fma_f32 v[2:3], v[20:21], v[2:3], v[64:65] op_sel:[0,0,0] op_sel_hi:[0,1,1]
	v_pk_fma_f32 v[60:61], v[30:31], v[8:9], v[60:61] op_sel:[1,0,0] op_sel_hi:[1,1,1]
	v_pk_fma_f32 v[4:5], v[20:21], v[4:5], v[14:15] op_sel:[1,0,0] op_sel_hi:[1,1,1]
	v_pk_mul_f32 v[64:65], v[26:27], v[36:37] op_sel:[0,0] op_sel_hi:[0,1]
	v_add_f32_dpp v60, v61, v60 quad_perm:[1,0,3,2] row_mask:0xf bank_mask:0xf bound_ctrl:1
	v_pk_mul_f32 v[14:15], v[26:27], v[36:37] op_sel:[1,0] op_sel_hi:[1,1]
	v_pk_fma_f32 v[6:7], v[22:23], v[6:7], v[64:65] op_sel:[0,0,0] op_sel_hi:[0,1,1]
	v_add_f32_dpp v60, v60, v60 quad_perm:[2,3,0,1] row_mask:0xf bank_mask:0xf bound_ctrl:1
	v_add_f32_dpp v62, v63, v62 quad_perm:[1,0,3,2] row_mask:0xf bank_mask:0xf bound_ctrl:1
	v_pk_fma_f32 v[8:9], v[22:23], v[8:9], v[14:15] op_sel:[1,0,0] op_sel_hi:[1,1,1]
	v_add_f32_dpp v60, v60, v60 row_half_mirror row_mask:0xf bank_mask:0xf bound_ctrl:1
	v_add_f32_dpp v62, v62, v62 quad_perm:[2,3,0,1] row_mask:0xf bank_mask:0xf bound_ctrl:1
	ds_read_b128 v[54:57], v250 offset:45568
	v_add_f32_dpp v60, v60, v60 row_mirror row_mask:0xf bank_mask:0xf bound_ctrl:1
	v_add_f32_dpp v62, v62, v62 row_half_mirror row_mask:0xf bank_mask:0xf bound_ctrl:1
	ds_read_b128 v[38:41], v250 offset:44544
	v_mov_b32_dpp v61, v60 quad_perm:[1,0,3,2] row_mask:0xf bank_mask:0xf bound_ctrl:1
	v_add_f32_dpp v62, v62, v62 row_mirror row_mask:0xf bank_mask:0xf bound_ctrl:1
	s_waitcnt lgkmcnt(8)
	v_pk_fma_f32 v[2:3], v[32:33], v[60:61], v[2:3] op_sel:[0,0,0] op_sel_hi:[0,1,1] neg_lo:[0,1,0] neg_hi:[0,1,0]
	v_pk_fma_f32 v[4:5], v[32:33], v[60:61], v[4:5] op_sel:[1,0,0] op_sel_hi:[1,1,1] neg_lo:[0,1,0] neg_hi:[0,1,0]
	v_mov_b32_dpp v63, v62 quad_perm:[1,0,3,2] row_mask:0xf bank_mask:0xf bound_ctrl:1
	v_pk_fma_f32 v[6:7], v[34:35], v[60:61], v[6:7] op_sel:[0,0,0] op_sel_hi:[0,1,1] neg_lo:[0,1,0] neg_hi:[0,1,0]
	v_cvt_pk_bf16_f32 v64, v62, v63
	v_pk_fma_f32 v[8:9], v[34:35], v[60:61], v[8:9] op_sel:[1,0,0] op_sel_hi:[1,1,1] neg_lo:[0,1,0] neg_hi:[0,1,0]
	ds_write_b32 v253, v64 offset:3456
	v_pk_mul_f32 v[62:63], v[16:17], v[2:3] op_sel:[0,0] op_sel_hi:[0,1]
	ds_read_b128 v[28:31], v250 offset:46848
	v_pk_fma_f32 v[62:63], v[16:17], v[4:5], v[62:63] op_sel:[1,0,0] op_sel_hi:[1,1,1]
	ds_read_b32 v36, v251 offset:47360
	v_pk_fma_f32 v[62:63], v[18:19], v[6:7], v[62:63] op_sel:[0,0,0] op_sel_hi:[0,1,1]
	ds_read_b32 v37, v252 offset:47360
	v_pk_fma_f32 v[62:63], v[18:19], v[8:9], v[62:63] op_sel:[1,0,0] op_sel_hi:[1,1,1]
	ds_read_b128 v[24:27], v250 offset:46592
	ds_read_b128 v[20:23], v250 offset:46336
	s_waitcnt lgkmcnt(8)
	v_pk_mul_f32 v[60:61], v[50:51], v[2:3] op_sel:[0,0] op_sel_hi:[0,1]
	v_pk_mul_f32 v[64:65], v[46:47], v[58:59] op_sel:[0,0] op_sel_hi:[0,1]
	v_pk_fma_f32 v[60:61], v[50:51], v[4:5], v[60:61] op_sel:[1,0,0] op_sel_hi:[1,1,1]
	v_pk_mul_f32 v[14:15], v[46:47], v[58:59] op_sel:[1,0] op_sel_hi:[1,1]
	v_pk_fma_f32 v[60:61], v[52:53], v[6:7], v[60:61] op_sel:[0,0,0] op_sel_hi:[0,1,1]
	v_pk_fma_f32 v[2:3], v[42:43], v[2:3], v[64:65] op_sel:[0,0,0] op_sel_hi:[0,1,1]
	v_pk_fma_f32 v[60:61], v[52:53], v[8:9], v[60:61] op_sel:[1,0,0] op_sel_hi:[1,1,1]
	v_pk_fma_f32 v[4:5], v[42:43], v[4:5], v[14:15] op_sel:[1,0,0] op_sel_hi:[1,1,1]
	v_pk_mul_f32 v[64:65], v[48:49], v[58:59] op_sel:[0,0] op_sel_hi:[0,1]
	v_add_f32_dpp v60, v61, v60 quad_perm:[1,0,3,2] row_mask:0xf bank_mask:0xf bound_ctrl:1
	v_pk_mul_f32 v[14:15], v[48:49], v[58:59] op_sel:[1,0] op_sel_hi:[1,1]
	v_pk_fma_f32 v[6:7], v[44:45], v[6:7], v[64:65] op_sel:[0,0,0] op_sel_hi:[0,1,1]
	v_add_f32_dpp v60, v60, v60 quad_perm:[2,3,0,1] row_mask:0xf bank_mask:0xf bound_ctrl:1
	v_add_f32_dpp v62, v63, v62 quad_perm:[1,0,3,2] row_mask:0xf bank_mask:0xf bound_ctrl:1
	v_pk_fma_f32 v[8:9], v[44:45], v[8:9], v[14:15] op_sel:[1,0,0] op_sel_hi:[1,1,1]
	v_add_f32_dpp v60, v60, v60 row_half_mirror row_mask:0xf bank_mask:0xf bound_ctrl:1
	v_add_f32_dpp v62, v62, v62 quad_perm:[2,3,0,1] row_mask:0xf bank_mask:0xf bound_ctrl:1
	ds_read_b128 v[32:35], v250 offset:47104
	v_add_f32_dpp v60, v60, v60 row_mirror row_mask:0xf bank_mask:0xf bound_ctrl:1
	v_add_f32_dpp v62, v62, v62 row_half_mirror row_mask:0xf bank_mask:0xf bound_ctrl:1
	ds_read_b128 v[16:19], v250 offset:46080
	v_mov_b32_dpp v61, v60 quad_perm:[1,0,3,2] row_mask:0xf bank_mask:0xf bound_ctrl:1
	v_add_f32_dpp v62, v62, v62 row_mirror row_mask:0xf bank_mask:0xf bound_ctrl:1
	s_waitcnt lgkmcnt(8)
; #define LAS __attribute__((address_space(3)))
; DI unsigned pk2(float a, float b) { f32x2 v = {a, b}; bf2_t r = __builtin_convertvector(v, bf2_t); return __builtin_bit_cast(unsigned, r); }
; DI f32x2 red16p(f32x2 x) { float a = x.x, b = x.y; red16x2(a, b); return (f32x2){a, b}; }
; DI void scan_bh2(const Args& a, int l, int bh, int halfsel, LAS unsigned char* lds) {
;     ...
;             for (int st = 0; st < T; ++st) {
;                 f32x4 nr4, nd4, nk4, nkk4, nb4; f32x2 nv2;
;                 if (st < T - 1) {
;                     const LAS float* o = cur + (st + 1) * 384;
;                     nr4 = *(const LAS f32x4*)(o + kq * 4); nd4 = *(const LAS f32x4*)(o + 64 + kq * 4); nk4 = *(const LAS f32x4*)(o + 128 + kq * 4);
;                     nkk4 = *(const LAS f32x4*)(o + 192 + kq * 4); nb4 = *(const LAS f32x4*)(o + 256 + kq * 4); nv2 = *(const LAS f32x2*)(o + 320 + row0);
;                 }
;                 f32x2 sa = S[0] * kk4[0]; sa += S[1] * kk4[1]; f32x2 sb = S[2] * kk4[2]; sb += S[3] * kk4[3]; sa += sb;
;                 sa = red16p(sa); sa = -sa;
; #pragma unroll
;                 for (int j = 0; j < 4; ++j) S[j] = S[j] * d4[j] + sa * b4[j] + v2 * k4[j];
;                 f32x2 y = S[0] * r4[0]; y += S[1] * r4[1]; f32x2 yc = S[2] * r4[2]; yc += S[3] * r4[3]; y += yc;
;                 y = red16p(y);
;                 *(LAS unsigned*)(yb + st * 128 + row0 * 2) = pk2(y.x, y.y);
;                 if (st < T - 1) { r4 = nr4; d4 = nd4; k4 = nk4; kk4 = nkk4; b4 = nb4; v2 = nv2; }
	v_pk_fma_f32 v[2:3], v[54:55], v[60:61], v[2:3] op_sel:[0,0,0] op_sel_hi:[0,1,1] neg_lo:[0,1,0] neg_hi:[0,1,0]
	v_pk_fma_f32 v[4:5], v[54:55], v[60:61], v[4:5] op_sel:[1,0,0] op_sel_hi:[1,1,1] neg_lo:[0,1,0] neg_hi:[0,1,0]
	v_mov_b32_dpp v63, v62 quad_perm:[1,0,3,2] row_mask:0xf bank_mask:0xf bound_ctrl:1
	v_pk_fma_f32 v[6:7], v[56:57], v[60:61], v[6:7] op_sel:[0,0,0] op_sel_hi:[0,1,1] neg_lo:[0,1,0] neg_hi:[0,1,0]
	v_cvt_pk_bf16_f32 v64, v62, v63
	v_pk_fma_f32 v[8:9], v[56:57], v[60:61], v[8:9] op_sel:[1,0,0] op_sel_hi:[1,1,1] neg_lo:[0,1,0] neg_hi:[0,1,0]
	ds_write_b32 v253, v64 offset:3584
	v_pk_mul_f32 v[62:63], v[38:39], v[2:3] op_sel:[0,0] op_sel_hi:[0,1]
	ds_read_b128 v[50:53], v250 offset:48384
	v_pk_fma_f32 v[62:63], v[38:39], v[4:5], v[62:63] op_sel:[1,0,0] op_sel_hi:[1,1,1]
	ds_read_b32 v58, v251 offset:48896
	v_pk_fma_f32 v[62:63], v[40:41], v[6:7], v[62:63] op_sel:[0,0,0] op_sel_hi:[0,1,1]
	ds_read_b32 v59, v252 offset:48896
	v_pk_fma_f32 v[62:63], v[40:41], v[8:9], v[62:63] op_sel:[1,0,0] op_sel_hi:[1,1,1]
	ds_read_b128 v[46:49], v250 offset:48128
	ds_read_b128 v[42:45], v250 offset:47872
	s_waitcnt lgkmcnt(8)
	v_pk_mul_f32 v[60:61], v[28:29], v[2:3] op_sel:[0,0] op_sel_hi:[0,1]
	v_pk_mul_f32 v[64:65], v[24:25], v[36:37] op_sel:[0,0] op_sel_hi:[0,1]
	v_pk_fma_f32 v[60:61], v[28:29], v[4:5], v[60:61] op_sel:[1,0,0] op_sel_hi:[1,1,1]
	v_pk_mul_f32 v[14:15], v[24:25], v[36:37] op_sel:[1,0] op_sel_hi:[1,1]
	v_pk_fma_f32 v[60:61], v[30:31], v[6:7], v[60:61] op_sel:[0,0,0] op_sel_hi:[0,1,1]
	v_pk_fma_f32 v[2:3], v[20:21], v[2:3], v[64:65] op_sel:[0,0,0] op_sel_hi:[0,1,1]
	v_pk_fma_f32 v[60:61], v[30:31], v[8:9], v[60:61] op_sel:[1,0,0] op_sel_hi:[1,1,1]
	v_pk_fma_f32 v[4:5], v[20:21], v[4:5], v[14:15] op_sel:[1,0,0] op_sel_hi:[1,1,1]
	v_pk_mul_f32 v[64:65], v[26:27], v[36:37] op_sel:[0,0] op_sel_hi:[0,1]
	v_add_f32_dpp v60, v61, v60 quad_perm:[1,0,3,2] row_mask:0xf bank_mask:0xf bound_ctrl:1
	v_pk_mul_f32 v[14:15], v[26:27], v[36:37] op_sel:[1,0] op_sel_hi:[1,1]
	v_pk_fma_f32 v[6:7], v[22:23], v[6:7], v[64:65] op_sel:[0,0,0] op_sel_hi:[0,1,1]
	v_add_f32_dpp v60, v60, v60 quad_perm:[2,3,0,1] row_mask:0xf bank_mask:0xf bound_ctrl:1
	v_add_f32_dpp v62, v63, v62 quad_perm:[1,0,3,2] row_mask:0xf bank_mask:0xf bound_ctrl:1
	v_pk_fma_f32 v[8:9], v[22:23], v[8:9], v[14:15] op_sel:[1,0,0] op_sel_hi:[1,1,1]
	v_add_f32_dpp v60, v60, v60 row_half_mirror row_mask:0xf bank_mask:0xf bound_ctrl:1
	v_add_f32_dpp v62, v62, v62 quad_perm:[2,3,0,1] row_mask:0xf bank_mask:0xf bound_ctrl:1
	ds_read_b128 v[54:57], v250 offset:48640
	v_add_f32_dpp v60, v60, v60 row_mirror row_mask:0xf bank_mask:0xf bound_ctrl:1
	v_add_f32_dpp v62, v62, v62 row_half_mirror row_mask:0xf bank_mask:0xf bound_ctrl:1
	ds_read_b128 v[38:41], v250 offset:47616
	v_mov_b32_dpp v61, v60 quad_perm:[1,0,3,2] row_mask:0xf bank_mask:0xf bound_ctrl:1
	v_add_f32_dpp v62, v62, v62 row_mirror row_mask:0xf bank_mask:0xf bound_ctrl:1
	s_waitcnt lgkmcnt(8)
	v_pk_fma_f32 v[2:3], v[32:33], v[60:61], v[2:3] op_sel:[0,0,0] op_sel_hi:[0,1,1] neg_lo:[0,1,0] neg_hi:[0,1,0]
	v_pk_fma_f32 v[4:5], v[32:33], v[60:61], v[4:5] op_sel:[1,0,0] op_sel_hi:[1,1,1] neg_lo:[0,1,0] neg_hi:[0,1,0]
	v_mov_b32_dpp v63, v62 quad_perm:[1,0,3,2] row_mask:0xf bank_mask:0xf bound_ctrl:1
	v_pk_fma_f32 v[6:7], v[34:35], v[60:61], v[6:7] op_sel:[0,0,0] op_sel_hi:[0,1,1] neg_lo:[0,1,0] neg_hi:[0,1,0]
	v_cvt_pk_bf16_f32 v64, v62, v63
	v_pk_fma_f32 v[8:9], v[34:35], v[60:61], v[8:9] op_sel:[1,0,0] op_sel_hi:[1,1,1] neg_lo:[0,1,0] neg_hi:[0,1,0]
	ds_write_b32 v253, v64 offset:3712
	v_pk_mul_f32 v[62:63], v[16:17], v[2:3] op_sel:[0,0] op_sel_hi:[0,1]
	s_nop 0
	v_pk_fma_f32 v[62:63], v[16:17], v[4:5], v[62:63] op_sel:[1,0,0] op_sel_hi:[1,1,1]
	s_nop 0
	v_pk_fma_f32 v[62:63], v[18:19], v[6:7], v[62:63] op_sel:[0,0,0] op_sel_hi:[0,1,1]
	s_nop 0
	v_pk_fma_f32 v[62:63], v[18:19], v[8:9], v[62:63] op_sel:[1,0,0] op_sel_hi:[1,1,1]
	s_waitcnt lgkmcnt(3)
; #define LAS __attribute__((address_space(3)))
; DI unsigned pk2(float a, float b) { f32x2 v = {a, b}; bf2_t r = __builtin_convertvector(v, bf2_t); return __builtin_bit_cast(unsigned, r); }
; DI f32x2 red16p(f32x2 x) { float a = x.x, b = x.y; red16x2(a, b); return (f32x2){a, b}; }
; DI void scan_bh2(const Args& a, int l, int bh, int halfsel, LAS unsigned char* lds) {
;     ...
;             for (int st = 0; st < T; ++st) {
;                 f32x4 nr4, nd4, nk4, nkk4, nb4; f32x2 nv2;
;                 if (st < T - 1) {
;                     const LAS float* o = cur + (st + 1) * 384;
;                     nr4 = *(const LAS f32x4*)(o + kq * 4); nd4 = *(const LAS f32x4*)(o + 64 + kq * 4); nk4 = *(const LAS f32x4*)(o + 128 + kq * 4);
;                     nkk4 = *(const LAS f32x4*)(o + 192 + kq * 4); nb4 = *(const LAS f32x4*)(o + 256 + kq * 4); nv2 = *(const LAS f32x2*)(o + 320 + row0);
;                 }
;                 f32x2 sa = S[0] * kk4[0]; sa += S[1] * kk4[1]; f32x2 sb = S[2] * kk4[2]; sb += S[3] * kk4[3]; sa += sb;
;                 sa = red16p(sa); sa = -sa;
; #pragma unroll
;                 for (int j = 0; j < 4; ++j) S[j] = S[j] * d4[j] + sa * b4[j] + v2 * k4[j];
;                 f32x2 y = S[0] * r4[0]; y += S[1] * r4[1]; f32x2 yc = S[2] * r4[2]; yc += S[3] * r4[3]; y += yc;
;                 y = red16p(y);
;                 *(LAS unsigned*)(yb + st * 128 + row0 * 2) = pk2(y.x, y.y);
;                 if (st < T - 1) { r4 = nr4; d4 = nd4; k4 = nk4; kk4 = nkk4; b4 = nb4; v2 = nv2; }
;             }
;             __syncthreads();
;             if (tid < T * 4) { const int rowi = tid >> 2, seg = tid & 3;
;                 *(u32x4*)(Y + ((size_t)b * SEQ + c * T + rowi) * 512 + h * 64 + halfsel * 32 + seg * 8) = *(const LAS u32x4*)(yb + rowi * 128 + halfsel * 64 + seg * 16); }
	v_pk_mul_f32 v[60:61], v[50:51], v[2:3] op_sel:[0,0] op_sel_hi:[0,1]
	v_pk_mul_f32 v[64:65], v[46:47], v[58:59] op_sel:[0,0] op_sel_hi:[0,1]
	v_pk_fma_f32 v[60:61], v[50:51], v[4:5], v[60:61] op_sel:[1,0,0] op_sel_hi:[1,1,1]
	v_pk_mul_f32 v[14:15], v[46:47], v[58:59] op_sel:[1,0] op_sel_hi:[1,1]
	v_pk_fma_f32 v[60:61], v[52:53], v[6:7], v[60:61] op_sel:[0,0,0] op_sel_hi:[0,1,1]
	v_pk_fma_f32 v[2:3], v[42:43], v[2:3], v[64:65] op_sel:[0,0,0] op_sel_hi:[0,1,1]
	v_pk_fma_f32 v[60:61], v[52:53], v[8:9], v[60:61] op_sel:[1,0,0] op_sel_hi:[1,1,1]
	v_pk_fma_f32 v[4:5], v[42:43], v[4:5], v[14:15] op_sel:[1,0,0] op_sel_hi:[1,1,1]
	v_pk_mul_f32 v[64:65], v[48:49], v[58:59] op_sel:[0,0] op_sel_hi:[0,1]
	v_add_f32_dpp v60, v61, v60 quad_perm:[1,0,3,2] row_mask:0xf bank_mask:0xf bound_ctrl:1
	v_pk_mul_f32 v[14:15], v[48:49], v[58:59] op_sel:[1,0] op_sel_hi:[1,1]
	v_pk_fma_f32 v[6:7], v[44:45], v[6:7], v[64:65] op_sel:[0,0,0] op_sel_hi:[0,1,1]
	v_add_f32_dpp v60, v60, v60 quad_perm:[2,3,0,1] row_mask:0xf bank_mask:0xf bound_ctrl:1
	v_add_f32_dpp v62, v63, v62 quad_perm:[1,0,3,2] row_mask:0xf bank_mask:0xf bound_ctrl:1
	v_pk_fma_f32 v[8:9], v[44:45], v[8:9], v[14:15] op_sel:[1,0,0] op_sel_hi:[1,1,1]
	v_add_f32_dpp v60, v60, v60 row_half_mirror row_mask:0xf bank_mask:0xf bound_ctrl:1
	v_add_f32_dpp v62, v62, v62 quad_perm:[2,3,0,1] row_mask:0xf bank_mask:0xf bound_ctrl:1
	s_nop 0
	v_add_f32_dpp v60, v60, v60 row_mirror row_mask:0xf bank_mask:0xf bound_ctrl:1
	v_add_f32_dpp v62, v62, v62 row_half_mirror row_mask:0xf bank_mask:0xf bound_ctrl:1
	s_nop 0
	v_mov_b32_dpp v61, v60 quad_perm:[1,0,3,2] row_mask:0xf bank_mask:0xf bound_ctrl:1
	v_add_f32_dpp v62, v62, v62 row_mirror row_mask:0xf bank_mask:0xf bound_ctrl:1
	s_waitcnt lgkmcnt(1)
	v_pk_fma_f32 v[2:3], v[54:55], v[60:61], v[2:3] op_sel:[0,0,0] op_sel_hi:[0,1,1] neg_lo:[0,1,0] neg_hi:[0,1,0]
	v_pk_fma_f32 v[4:5], v[54:55], v[60:61], v[4:5] op_sel:[1,0,0] op_sel_hi:[1,1,1] neg_lo:[0,1,0] neg_hi:[0,1,0]
	v_mov_b32_dpp v63, v62 quad_perm:[1,0,3,2] row_mask:0xf bank_mask:0xf bound_ctrl:1
	v_pk_fma_f32 v[6:7], v[56:57], v[60:61], v[6:7] op_sel:[0,0,0] op_sel_hi:[0,1,1] neg_lo:[0,1,0] neg_hi:[0,1,0]
	v_cvt_pk_bf16_f32 v64, v62, v63
	v_pk_fma_f32 v[8:9], v[56:57], v[60:61], v[8:9] op_sel:[1,0,0] op_sel_hi:[1,1,1] neg_lo:[0,1,0] neg_hi:[0,1,0]
	ds_write_b32 v253, v64 offset:3840
	v_pk_mul_f32 v[62:63], v[38:39], v[2:3] op_sel:[0,0] op_sel_hi:[0,1]
	s_nop 0
	v_pk_fma_f32 v[62:63], v[38:39], v[4:5], v[62:63] op_sel:[1,0,0] op_sel_hi:[1,1,1]
	s_nop 0
	v_pk_fma_f32 v[62:63], v[40:41], v[6:7], v[62:63] op_sel:[0,0,0] op_sel_hi:[0,1,1]
	s_nop 0
	v_pk_fma_f32 v[62:63], v[40:41], v[8:9], v[62:63] op_sel:[1,0,0] op_sel_hi:[1,1,1]
	s_nop 1
	v_add_f32_dpp v62, v63, v62 quad_perm:[1,0,3,2] row_mask:0xf bank_mask:0xf bound_ctrl:1
	s_nop 1
	v_add_f32_dpp v62, v62, v62 quad_perm:[2,3,0,1] row_mask:0xf bank_mask:0xf bound_ctrl:1
	s_nop 1
	v_add_f32_dpp v62, v62, v62 row_half_mirror row_mask:0xf bank_mask:0xf bound_ctrl:1
	s_nop 1
	v_add_f32_dpp v62, v62, v62 row_mirror row_mask:0xf bank_mask:0xf bound_ctrl:1
	s_nop 1
	v_mov_b32_dpp v63, v62 quad_perm:[1,0,3,2] row_mask:0xf bank_mask:0xf bound_ctrl:1
	v_cvt_pk_bf16_f32 v64, v62, v63
	ds_write_b32 v253, v64 offset:3968
	s_waitcnt lgkmcnt(0)
	s_barrier
	s_and_saveexec_b64 s[2:3], vcc
	s_cbranch_execz .LBB0_496
	v_readlane_b32 s6, v247, 9
	s_add_i32 s5, s6, s5
	v_add3_u32 v14, s5, v13, v128
	ds_read_b128 v[14:17], v14
	s_waitcnt lgkmcnt(0)
	global_store_dwordx4 v[0:1], v[14:17], off
	s_branch .LBB0_496
